# mixer-A units of layer 0 also dealt behind the M2 queue (384 of 512), as in layer 1
# speedup vs baseline: 1.0006x; 1.0006x over previous
; #define LAS __attribute__((address_space(3)))
; __device__ __forceinline__ unsigned xb_add(unsigned* p, unsigned v) { return __hip_atomic_fetch_add(p, v, __ATOMIC_RELAXED, __HIP_MEMORY_SCOPE_AGENT); }
; __device__ __forceinline__ unsigned xb_xcc_id() { return (unsigned)__builtin_amdgcn_s_getreg((3 << 11) | 20) & 0xFu; }
; #define CAS __attribute__((address_space(4)))
;     __device__ __forceinline__ unsigned* ctl() const { return (unsigned*)(pp->ws + WS_CTL); }
; #define RETID() do { int _l; asm volatile("v_mbcnt_lo_u32_b32 %0, -1, 0\n\tv_mbcnt_hi_u32_b32 %0, -1, %0" : "=v"(_l)); c.lane = _l; c.tid = c.wave * 64 + _l; } while (0)
; __device__ __forceinline__ XcdBarrier xcd_barrier_post(unsigned* bar, volatile LAS unsigned* st, const bool t0  ) {
;     XcdBarrier b; b.bar = bar; b.x = xb_xcc_id(); b.st = st;
;     if (t0) (void)xb_add(&bar[XB_XCNT(b.x)], 1u);
;     return b;
; __global__ void __launch_bounds__(512, 2) hybrid_fwd(Params P) {
;     ...
;         c.pp = (const CAS Params*)__builtin_amdgcn_kernarg_segment_ptr();
;     c.lds = (LAS unsigned char*)lds_raw;
;     c.wave = __builtin_amdgcn_readfirstlane((int)(threadIdx.x >> 6));
;     ...
;     RETID();
;     if (c.tid < 32) ((LAS unsigned*)(c.lds + LDS_CTL))[c.tid] = 0u;
;     __syncthreads();
;     const int lo = P.ph_lo, hi = P.ph_hi;
;     XcdBarrier bar; bar.bar = c.ctl() + CW_BAR; bar.x = 0; bar.st = (volatile LAS unsigned*)(c.lds + LDS_CTL);
;     if (hi > lo) bar = xcd_barrier_post(c.ctl() + CW_BAR, (volatile LAS unsigned*)(c.lds + LDS_CTL), c.tid == 0);
_Z10hybrid_fwd6Params:
	v_writelane_b32 v255, 0, 62
	v_writelane_b32 v255, 0, 61
	v_readfirstlane_b32 s4, v0
	v_writelane_b32 v250, s0, 0
	s_and_b32 s33, s4, 0xffffffc0
	v_mbcnt_lo_u32_b32 v0, -1, 0
	v_mbcnt_hi_u32_b32 v0, -1, v0
	s_mov_b32 s39, s2
	v_writelane_b32 v250, s1, 1
	s_load_dwordx2 s[0:1], s[0:1], 0xc8
	v_add_u32_e32 v173, s33, v0
	v_cmp_gt_i32_e32 vcc, 32, v173
	s_waitcnt lgkmcnt(0)
	v_writelane_b32 v250, s0, 2
	s_nop 1
	v_writelane_b32 v250, s1, 3
	s_and_saveexec_b64 s[0:1], vcc
	v_lshl_add_u32 v0, v173, 2, 0
	v_add_u32_e32 v0, 0x27f00, v0
	v_mov_b32_e32 v1, 0
	ds_write_b32 v0, v1
	s_or_b64 exec, exec, s[0:1]
	v_readlane_b32 s0, v250, 0
	v_readlane_b32 s1, v250, 1
	s_waitcnt lgkmcnt(0)
	s_barrier
	s_load_dwordx2 s[0:1], s[0:1], 0xc0
	s_waitcnt lgkmcnt(0)
	v_writelane_b32 v250, s0, 4
	s_nop 1
	v_writelane_b32 v250, s1, 5
	s_nop 0
	v_readlane_b32 s0, v250, 2
	v_readlane_b32 s1, v250, 3
	s_cmp_le_i32 s1, s0
	s_mov_b32 s0, 0
	v_writelane_b32 v250, s0, 6
	s_cbranch_scc1 .LBB0_7
	s_getreg_b32 s0, hwreg(HW_REG_XCC_ID, 0, 4)
	s_and_b32 s0, s0, 15
	v_cmp_eq_u32_e32 vcc, 0, v173
	v_writelane_b32 v250, s0, 6
	s_and_saveexec_b64 s[0:1], vcc
	s_cbranch_execz .LBB0_6
	s_mov_b64 s[2:3], exec
	v_mbcnt_lo_u32_b32 v0, s2, 0
	v_mbcnt_hi_u32_b32 v0, s3, v0
	v_cmp_eq_u32_e32 vcc, 0, v0
	s_and_b64 s[6:7], exec, vcc
	s_mov_b64 exec, s[6:7]
	s_cbranch_execz .LBB0_6
	v_readlane_b32 s5, v250, 6
	s_lshl_b32 s5, s5, 8
	v_readlane_b32 s6, v250, 4
	v_readlane_b32 s7, v250, 5
	s_add_u32 s6, s6, s5
	s_addc_u32 s7, s7, 0
	s_bcnt1_i32_b64 s2, s[2:3]
	v_mov_b32_e32 v0, 0x4000
	v_mov_b32_e32 v1, s2
	global_atomic_add v0, v1, s[6:7] offset:1024

; #define RETID() do { int _l; asm volatile("v_mbcnt_lo_u32_b32 %0, -1, 0\n\tv_mbcnt_hi_u32_b32 %0, -1, %0" : "=v"(_l)); c.lane = _l; c.tid = c.wave * 64 + _l; } while (0)
; __global__ void __launch_bounds__(512, 2) hybrid_fwd(Params P) {
;     ...
;     RETID();
.LBB0_1029:
	v_readlane_b32 s2, v250, 2
	v_readlane_b32 s3, v250, 3
	s_cmp_lt_i32 s2, 4
	s_cselect_b64 s[2:3], -1, 0
	s_and_b64 s[2:3], s[2:3], s[0:1]
	s_andn2_b64 vcc, exec, s[2:3]
	s_lshl_b32 s24, s36, 6
	v_mbcnt_lo_u32_b32 v0, -1, 0
	v_mbcnt_hi_u32_b32 v0, -1, v0
	s_cbranch_vccnz .LBB0_1286
; #define LAS __attribute__((address_space(3)))
; __device__ __forceinline__ void mixA_unit(const Ctx& c, int l, int a) {
;     const int b = a >> 7, chunk = (a >> 3) & 15, hh = a & 7, r0 = b * 2048 + chunk * 128;
;     LAS unsigned char* WmB = opq(c.lds);
;     LAS unsigned char* vT = opq(c.lds + 36864);
;     LAS float* mixed = opq((LAS float*)(c.lds + 73728));
;     LAS float* st_mean = opq((LAS float*)(c.lds + 73728 + 67584));
;     LAS float* st_rstd = st_mean + 128;
;     const bf16* VA = c.w<bf16>(WS_VA) + (size_t)r0 * 1024; const bf16* UA = c.w<bf16>(WS_UA) + (size_t)r0 * 1024; const bf16* ZA = c.w<bf16>(WS_ZA) + (size_t)r0 * 1024;
;     const int lane = c.lane, wave = c.wave, m = lane & 15, quad = lane >> 4;
; #pragma unroll
;     for (int half = 0; half < 2; ++half) {
;         u32x4 raw[8][2];
; #pragma unroll
;         for (int i = 0; i < 8; ++i) { const bf16* row = VA + (size_t)(wave * 16 + half * 8 + i) * 1024; raw[i][0] = *(const u32x4*)(row + lane * 8); raw[i][1] = *(const u32x4*)(row + 512 + lane * 8); }
; __device__ __forceinline__ void dprep_unit(const Ctx& c, int l, int b, int chunk, int h) {
;     LAS unsigned char* qs = opq(c.lds);
;     LAS unsigned char* ks = opq(c.lds + 18432);
;     LAS float* rhs = opq((LAS float*)(c.lds + 36864));
;     LAS float* a_s = opq((LAS float*)(c.lds + 102400));
;     LAS unsigned char* kgT = opq(c.lds + 118784);
;     LAS float* Gs = opq((LAS float*)(c.lds + 139264));
;     LAS float* betas = Gs + 64;
;     unsigned char* rec = c.ws() + WS_REC + (size_t)((b * 16 + h) * 32 + chunk) * REC_BYTES;
;     const int lane = c.lane, wave = c.wave, m = lane & 15, quad = lane >> 4;
;     const int row0 = b * 2048 + chunk * 64;
;     const bf16* base = c.w<bf16>(WS_QKVB) + (size_t)(b * 2048) * 6144 + h * 128 + 2 * lane;
;     const int t0 = chunk * 64 + 8 * wave;
;     unsigned xq[11], xk[11], xv[11];
; #pragma unroll
;     for (int jr = 0; jr < 11; ++jr) {
;         const int p = t0 - 3 + jr;
;         if (p >= 0) { const bf16* rp = base + (size_t)p * 6144; xq[jr] = *(const unsigned*)rp; xk[jr] = *(const unsigned*)(rp + 2048); xv[jr] = *(const unsigned*)(rp + 4096); }
;         else { xq[jr] = 0u; xk[jr] = 0u; xv[jr] = 0u; }
;     }
;     float wq[4][2], wk[4][2], wv[4][2];
;     const float* cw = c.f(I_CONVW) + (size_t)l * 4 * 6144 + h * 128 + 2 * lane;
; #pragma unroll
	s_lshl_b32 s8, s36, 4
	v_writelane_b32 v250, s2, 42
	s_ashr_i32 s9, s8, 31
	s_lshl_b64 s[0:1], s[8:9], 11
	v_writelane_b32 v250, s3, 43
	v_writelane_b32 v250, s0, 44
	s_mul_i32 s25, s36, 3
	v_readlane_b32 vcc_lo, v255, 61
	s_nop 3
	v_mov_b32_e32 v222, vcc_lo
	v_lshlrev_b32_e32 v222, 12, v222
	v_add_u32_e32 v222, 0x10000, v222
	v_writelane_b32 v250, s1, 45
	s_or_b32 s0, s8, 1
	s_ashr_i32 s1, s0, 31
	s_lshl_b64 s[0:1], s[0:1], 11
	v_writelane_b32 v250, s0, 46
	s_mov_b32 s27, 0x12000
	v_mov_b32_e32 v17, 0
	v_writelane_b32 v250, s1, 47
	s_or_b32 s0, s8, 2
	s_ashr_i32 s1, s0, 31
	s_lshl_b64 s[0:1], s[0:1], 11
	v_writelane_b32 v250, s0, 48
	v_mov_b32_e32 v223, 0x3ecc95a3
	v_mov_b32_e32 v224, 0x16000
	v_writelane_b32 v250, s1, 49
	s_or_b32 s0, s8, 3
	s_ashr_i32 s1, s0, 31
	s_lshl_b64 s[0:1], s[0:1], 11
	v_writelane_b32 v250, s0, 50
	v_mov_b32_e32 v225, 0x358637bd
	v_mov_b32_e32 v226, 0x3000
	v_writelane_b32 v250, s1, 51
	s_or_b32 s0, s8, 4
	s_ashr_i32 s1, s0, 31
	s_lshl_b64 s[0:1], s[0:1], 11
	v_writelane_b32 v250, s0, 52
	v_mov_b32_e32 v138, 0x7f800000
	v_mov_b32_e32 v228, 0x3f317218
	v_writelane_b32 v250, s1, 53
	s_or_b32 s0, s8, 5
	s_ashr_i32 s1, s0, 31
	s_lshl_b64 s[0:1], s[0:1], 11
	v_writelane_b32 v250, s0, 54
	v_mov_b32_e32 v139, 0xff800000
	v_bfrev_b32_e32 v140, 1
	v_writelane_b32 v250, s1, 55
	s_or_b32 s0, s8, 6
	s_ashr_i32 s1, s0, 31
	s_lshl_b64 s[0:1], s[0:1], 11
	v_writelane_b32 v250, s0, 56
	s_mov_b32 s28, 0x800000
	s_movk_i32 s33, 0x7fff
	v_writelane_b32 v250, s1, 57
	s_or_b32 s0, s8, 7
	s_ashr_i32 s1, s0, 31
	s_lshl_b64 s[0:1], s[0:1], 11
	v_writelane_b32 v250, s0, 58
	s_mov_b32 s29, 0x41a00000
	s_mov_b32 s30, 0x3fb8aa3b
	v_writelane_b32 v250, s1, 59
	s_or_b32 s0, s8, 8
	s_ashr_i32 s1, s0, 31
	s_lshl_b64 s[0:1], s[0:1], 11
	v_writelane_b32 v250, s0, 60
	s_mov_b32 s31, 0xc2ce8ed0
	s_mov_b32 s40, 0x42b17218
	v_writelane_b32 v250, s1, 61
	s_or_b32 s0, s8, 9
	s_ashr_i32 s1, s0, 31
	s_lshl_b64 s[0:1], s[0:1], 11
	v_writelane_b32 v250, s0, 62
	s_mov_b32 s38, 0xbfb8aa3b
	s_mov_b32 s41, 0x42ce8ed0
	v_writelane_b32 v250, s1, 63
	s_or_b32 s0, s8, 10
	s_ashr_i32 s1, s0, 31
	s_lshl_b64 s[0:1], s[0:1], 11
	v_writelane_b32 v251, s0, 0
	s_mov_b32 s42, 0xc2b17218
	s_mov_b32 s43, 0x10100
	v_writelane_b32 v251, s1, 1
	s_or_b32 s0, s8, 11
	s_ashr_i32 s1, s0, 31
	s_lshl_b64 s[0:1], s[0:1], 11
	v_writelane_b32 v251, s0, 2
	s_mov_b32 s17, 0
	s_mov_b32 s68, 0x3d000000
	v_writelane_b32 v251, s1, 3
	s_or_b32 s0, s8, 12
	s_ashr_i32 s1, s0, 31
	s_lshl_b64 s[0:1], s[0:1], 11
	v_writelane_b32 v251, s0, 4
	s_nop 1
	v_writelane_b32 v251, s1, 5
	s_or_b32 s0, s8, 13
	s_ashr_i32 s1, s0, 31
	s_lshl_b64 s[0:1], s[0:1], 11
	v_writelane_b32 v251, s0, 6
	s_nop 1
	v_writelane_b32 v251, s1, 7
	s_or_b32 s0, s8, 14
	s_ashr_i32 s1, s0, 31
	s_lshl_b64 s[0:1], s[0:1], 11
	v_writelane_b32 v251, s0, 8
	s_nop 1
	v_writelane_b32 v251, s1, 9
	s_or_b32 s0, s8, 15
	s_ashr_i32 s1, s0, 31
	s_lshl_b64 s[0:1], s[0:1], 11
	v_writelane_b32 v251, s0, 10
	s_nop 1
	v_writelane_b32 v251, s1, 11
	s_ashr_i32 s0, s36, 1
	s_cmp_gt_i32 s0, -1
	s_cselect_b64 s[2:3], -1, 0
	v_writelane_b32 v251, s2, 12
	s_cmp_gt_i32 s0, 0
	s_nop 0
	v_writelane_b32 v251, s3, 13
	s_cselect_b64 s[2:3], -1, 0
	v_writelane_b32 v251, s2, 14
	s_cmp_gt_i32 s0, 1
	s_nop 0
	v_writelane_b32 v251, s3, 15
	s_cselect_b64 s[2:3], -1, 0
	v_writelane_b32 v251, s2, 16
	s_cmp_gt_i32 s0, 2
	s_cselect_b64 s[0:1], -1, 0
	v_writelane_b32 v251, s3, 17
	v_writelane_b32 v251, s0, 18
	s_lshl_b32 s6, s36, 3
	s_nop 0
	v_writelane_b32 v251, s1, 19
	s_add_i32 s0, s6, -3
	v_writelane_b32 v251, s0, 20
	s_cmp_eq_u32 s36, 0
	s_mul_i32 s0, s36, 0x240
	s_cselect_b64 s[34:35], -1, 0
	v_writelane_b32 v251, s0, 21
	s_lshl_b32 s0, s36, 13
	v_writelane_b32 v251, s0, 22
	s_or_b32 s0, s6, 1
	s_mul_i32 s7, s0, 0x48
	s_lshl_b32 s1, s0, 10
	v_writelane_b32 v251, s1, 23
	s_or_b32 s1, s6, 2
	s_add_i32 s2, s7, 0x48
	v_writelane_b32 v251, s2, 24
	s_lshl_b32 s2, s1, 10
	v_writelane_b32 v251, s2, 25
	s_or_b32 s2, s6, 3
	s_add_i32 s3, s7, 0x90
	v_writelane_b32 v251, s3, 26
	s_lshl_b32 s3, s2, 10
	v_writelane_b32 v251, s3, 27
	s_or_b32 s3, s6, 4
	s_add_i32 s4, s7, 0xd8
	v_writelane_b32 v251, s4, 28
	s_lshl_b32 s4, s3, 10
	v_writelane_b32 v251, s4, 29
	s_or_b32 s4, s6, 5
	s_add_i32 s5, s7, 0x120
	v_writelane_b32 v251, s5, 30
	s_lshl_b32 s5, s4, 10
	v_writelane_b32 v251, s5, 31
	s_or_b32 s5, s6, 6
	s_add_i32 s10, s7, 0x168
	v_writelane_b32 v251, s10, 32
	s_lshl_b32 s10, s5, 10
	v_writelane_b32 v251, s10, 33
	v_writelane_b32 v251, s6, 34
	s_or_b32 s6, s6, 7
	v_writelane_b32 v251, s7, 35
	s_addk_i32 s7, 0x1b0
	v_writelane_b32 v251, s7, 36
	s_lshl_b32 s7, s6, 10
	s_cmp_lt_u32 s36, 4
	v_writelane_b32 v251, s7, 37
	s_cselect_b64 s[10:11], -1, 0
	v_writelane_b32 v251, s10, 38
	s_cmp_gt_u32 s36, 3
	s_mul_i32 s0, s0, -6
	v_writelane_b32 v251, s11, 39
	s_cselect_b64 s[10:11], -1, 0
	v_writelane_b32 v251, s8, 40
	s_and_b32 s7, s8, 48
	s_cmp_lt_i32 s36, 4
	v_writelane_b32 v251, s9, 41
	v_writelane_b32 v251, s7, 42
	s_cselect_b64 s[8:9], -1, 0
	v_writelane_b32 v251, s8, 43
	s_cmp_gt_i32 s36, 3
	v_writelane_b32 v250, s10, 20
	v_writelane_b32 v251, s9, 44
	s_cselect_b64 s[8:9], -1, 0
	v_writelane_b32 v251, s8, 45
	s_lshl_b32 s7, s36, 5
	s_ashr_i32 s37, s36, 31
	v_writelane_b32 v251, s9, 46
	v_writelane_b32 v251, s7, 47
	s_and_b32 s7, s7, 0x60
	v_writelane_b32 v251, s7, 48
	s_lshl_b32 s7, s36, 1
	v_writelane_b32 v251, s7, 49
	s_lshl_b32 s7, s36, 14
	s_add_i32 s7, s7, 0
	v_writelane_b32 v251, s7, 50
	v_writelane_b32 v251, s0, 51
	s_mul_i32 s0, s1, -6
	v_writelane_b32 v251, s0, 52
	s_mul_i32 s0, s2, -6
	v_writelane_b32 v251, s0, 53
	s_mul_i32 s0, s3, -6
	v_writelane_b32 v251, s0, 54
	s_mul_i32 s0, s4, -6
	v_writelane_b32 v251, s0, 55
	s_mul_i32 s0, s5, -6
	v_writelane_b32 v251, s0, 56
	s_mul_i32 s0, s6, -6
	v_writelane_b32 v251, s0, 57
	s_and_b32 s0, s36, 3
	s_mul_i32 s1, s0, 0x880
	s_add_i32 s2, s1, 0x180
	v_writelane_b32 v251, s2, 58
	s_add_i32 s2, s1, 0x100
	v_writelane_b32 v251, s2, 59
	s_addk_i32 s1, 0x80
	v_writelane_b32 v251, s1, 60
	s_lshl_b32 s0, s0, 12
	v_writelane_b32 v251, s0, 61
	s_lshl_b32 s0, s36, 10
	s_addk_i32 s0, 0xf000
	v_writelane_b32 v251, s0, 62
	s_add_i32 s0, 0, 0x9000
	v_writelane_b32 v251, s0, 63
	s_add_i32 s0, 0, 0x12000
	v_writelane_b32 v252, s0, 0
	s_add_i32 s0, 0, 0x22800
	v_writelane_b32 v252, s0, 1
	s_add_i32 s0, 0, 0x4800
	v_writelane_b32 v252, s0, 2
	s_add_i32 s0, 0, 0x19000
	v_writelane_b32 v252, s0, 3
	s_add_i32 s0, 0, 0x1d000
	v_writelane_b32 v252, s0, 4
	s_add_i32 s0, 0, 0x22000
	v_writelane_b32 v252, s0, 5
	s_lshl_b64 s[0:1], s[36:37], 11
	v_writelane_b32 v252, s0, 6
	v_writelane_b32 v250, s11, 21
	s_add_i32 s26, 0, 0x27f40
	v_writelane_b32 v252, s1, 7
	v_writelane_b32 v252, s24, 8
	v_writelane_b32 v252, s34, 9
	s_mov_b32 s0, s36
	v_writelane_b32 v250, s0, 12
	v_writelane_b32 v252, s35, 10
	v_writelane_b32 v252, s25, 11
	v_mov_b32_e32 v136, s26
	v_writelane_b32 v250, s1, 13
	v_writelane_b32 v252, s26, 12
	s_branch .LBB0_1035

; #define LAS __attribute__((address_space(3)))
;     template <class T> __device__ __forceinline__ T* w(size_t off) const { return (T*)(pp->ws + off); }
; __device__ __forceinline__ float wave_sum(float v) { v = row16_sum(v); return (rlf(v, 0) + rlf(v, 16)) + (rlf(v, 32) + rlf(v, 48)); }
; template <class T> __device__ __forceinline__ LAS T* opq(LAS T* p) { asm volatile("" : "+v"(p)); return p; }
; __device__ __forceinline__ void mixA_unit(const Ctx& c, int l, int a) {
;     const int b = a >> 7, chunk = (a >> 3) & 15, hh = a & 7, r0 = b * 2048 + chunk * 128;
;     LAS unsigned char* WmB = opq(c.lds);
;     LAS unsigned char* vT = opq(c.lds + 36864);
;     LAS float* mixed = opq((LAS float*)(c.lds + 73728));
;     LAS float* st_mean = opq((LAS float*)(c.lds + 73728 + 67584));
;     LAS float* st_rstd = st_mean + 128;
;     const bf16* VA = c.w<bf16>(WS_VA) + (size_t)r0 * 1024; const bf16* UA = c.w<bf16>(WS_UA) + (size_t)r0 * 1024; const bf16* ZA = c.w<bf16>(WS_ZA) + (size_t)r0 * 1024;
;     const int lane = c.lane, wave = c.wave, m = lane & 15, quad = lane >> 4;
; #pragma unroll
;     for (int half = 0; half < 2; ++half) {
;         u32x4 raw[8][2];
; #pragma unroll
;         for (int i = 0; i < 8; ++i) { const bf16* row = VA + (size_t)(wave * 16 + half * 8 + i) * 1024; raw[i][0] = *(const u32x4*)(row + lane * 8); raw[i][1] = *(const u32x4*)(row + 512 + lane * 8); }
; #pragma unroll
;         for (int i = 0; i < 8; ++i) {
;             float x[8], y[8]; unpack8(raw[i][0], x); unpack8(raw[i][1], y);
;             float sm = 0.f, sq = 0.f;
; #pragma unroll
;             for (int e = 0; e < 8; ++e) { sm += x[e] + y[e]; sq += x[e] * x[e] + y[e] * y[e]; }
;             sm = wave_sum(sm); sq = wave_sum(sq);
; __device__ __forceinline__ void phase_M1(Ctx& c, int l, int q, const XcdBarrier& bar) {
;     ...
;         const int u = next_unit(c, q);
;         if (u >= M1_TOTAL) break;
.LBB0_1039:
	s_or_b64 exec, exec, s[0:1]
	s_waitcnt lgkmcnt(0)
	s_barrier
	ds_read_b32 v0, v136
	s_mov_b64 s[0:1], -1
	s_waitcnt lgkmcnt(0)
	v_readfirstlane_b32 s37, v0
	v_readlane_b32 s44, v255, 61
	s_nop 3
	s_mul_i32 s45, s44, 0x610
	s_add_i32 s37, s37, s45
	s_mul_i32 s45, s44, 0x180
	s_addk_i32 s45, 0x60f
	s_cmp_gt_i32 s37, s45
	s_cbranch_scc1 .LBB0_1034
	s_cmp_gt_i32 s37, 15
	s_cbranch_scc0 .LBB0_1124
	s_cmpk_gt_u32 s37, 0x10f
	s_cbranch_scc0 .LBB0_1103
	s_cmpk_gt_u32 s37, 0x18f
	s_cbranch_scc0 .LBB0_1090
	s_cmpk_gt_u32 s37, 0x58f
	s_cbranch_scc0 .LBB0_1086
	s_lshl_b32 s0, s37, 4
	s_addk_i32 s0, 0x700
	s_and_b32 s10, s0, 0x1f80
	v_readlane_b32 s0, v251, 63
	v_mov_b32_e32 v60, v17
	v_lshlrev_b32_e32 v58, 3, v66
	v_mov_b32_e32 v63, s0
	v_readlane_b32 s0, v252, 0
	v_ashrrev_i32_e32 v59, 31, v58
	v_lshlrev_b64 v[68:69], 1, v[58:59]
	v_mov_b32_e32 v61, s0
	v_readlane_b32 s0, v252, 1
	v_readlane_b32 s2, v251, 40
	v_cmp_eq_u32_e32 vcc, 0, v66
	v_mov_b32_e32 v65, s0
	s_load_dwordx2 s[4:5], s[90:91], 0xc0
	s_lshl_b32 s0, s10, 11
	v_readlane_b32 s3, v251, 41
	s_waitcnt lgkmcnt(0)
	s_add_u32 s0, s4, s0
	s_addc_u32 s1, s5, 0
	s_add_u32 s6, s0, 0x24700000
	s_addc_u32 s7, s1, 0
	v_readlane_b32 s0, v250, 44
	v_readlane_b32 s1, v250, 45
	s_add_u32 s0, s6, s0
	s_addc_u32 s1, s7, s1
	v_lshl_add_u64 v[0:1], s[0:1], 0, v[68:69]
	global_load_dwordx4 v[70:73], v[0:1], off
	global_load_dwordx4 v[74:77], v[0:1], off offset:1024
	v_readlane_b32 s0, v250, 46
	v_readlane_b32 s1, v250, 47
	s_add_u32 s0, s6, s0
	s_addc_u32 s1, s7, s1
	v_lshl_add_u64 v[0:1], s[0:1], 0, v[68:69]
	v_readlane_b32 s0, v250, 48
	v_readlane_b32 s1, v250, 49
	s_add_u32 s0, s6, s0
	s_addc_u32 s1, s7, s1
	global_load_dwordx4 v[54:57], v[0:1], off
	global_load_dwordx4 v[50:53], v[0:1], off offset:1024
	v_lshl_add_u64 v[0:1], s[0:1], 0, v[68:69]
	v_readlane_b32 s0, v250, 50
	v_readlane_b32 s1, v250, 51
	s_add_u32 s0, s6, s0
	s_addc_u32 s1, s7, s1
	global_load_dwordx4 v[46:49], v[0:1], off
	global_load_dwordx4 v[42:45], v[0:1], off offset:1024
	v_lshl_add_u64 v[0:1], s[0:1], 0, v[68:69]
	v_readlane_b32 s0, v250, 52
	v_readlane_b32 s1, v250, 53
	s_add_u32 s0, s6, s0
	s_addc_u32 s1, s7, s1
	global_load_dwordx4 v[38:41], v[0:1], off
	global_load_dwordx4 v[34:37], v[0:1], off offset:1024
	v_lshl_add_u64 v[0:1], s[0:1], 0, v[68:69]
	v_readlane_b32 s0, v250, 54
	v_readlane_b32 s1, v250, 55
	s_add_u32 s0, s6, s0
	s_addc_u32 s1, s7, s1
	global_load_dwordx4 v[30:33], v[0:1], off
	global_load_dwordx4 v[26:29], v[0:1], off offset:1024
	v_lshl_add_u64 v[0:1], s[0:1], 0, v[68:69]
	v_readlane_b32 s0, v250, 56
	v_readlane_b32 s1, v250, 57
	s_add_u32 s0, s6, s0
	s_addc_u32 s1, s7, s1
	global_load_dwordx4 v[22:25], v[0:1], off
	global_load_dwordx4 v[18:21], v[0:1], off offset:1024
	v_lshl_add_u64 v[0:1], s[0:1], 0, v[68:69]
	v_readlane_b32 s0, v250, 58
	v_readlane_b32 s1, v250, 59
	s_add_u32 s0, s6, s0
	s_addc_u32 s1, s7, s1
	global_load_dwordx4 v[12:15], v[0:1], off
	global_load_dwordx4 v[8:11], v[0:1], off offset:1024
	v_lshl_add_u64 v[0:1], s[0:1], 0, v[68:69]
	global_load_dwordx4 v[4:7], v[0:1], off
	s_nop 0
	global_load_dwordx4 v[0:3], v[0:1], off offset:1024
	s_waitcnt vmcnt(15)
	v_lshlrev_b32_e32 v16, 16, v70
	s_waitcnt vmcnt(14)
	v_lshlrev_b32_e32 v79, 16, v74
	v_and_b32_e32 v59, 0xffff0000, v70
	v_and_b32_e32 v74, 0xffff0000, v74
	v_add_f32_e32 v83, v16, v79
	v_mul_f32_e32 v79, v79, v79
	v_fmac_f32_e32 v79, v16, v16
	v_add_f32_e32 v16, v59, v74
	v_mul_f32_e32 v74, v74, v74
	v_lshlrev_b32_e32 v67, 16, v71
	v_lshlrev_b32_e32 v80, 16, v75
	v_add_f32_e32 v83, 0, v83
	v_fmac_f32_e32 v74, v59, v59
	v_add_f32_e32 v16, v16, v83
	v_add_f32_e32 v59, v79, v74
	v_add_f32_e32 v74, v67, v80
	v_and_b32_e32 v70, 0xffff0000, v71
	v_and_b32_e32 v75, 0xffff0000, v75
	v_add_f32_e32 v16, v74, v16
	v_mul_f32_e32 v74, v80, v80
	v_fmac_f32_e32 v74, v67, v67
	v_add_f32_e32 v67, v70, v75
	v_add_f32_e32 v16, v67, v16
	v_mul_f32_e32 v67, v75, v75
	v_lshlrev_b32_e32 v71, 16, v72
	v_lshlrev_b32_e32 v81, 16, v76
	v_add_f32_e32 v59, v74, v59
	v_fmac_f32_e32 v67, v70, v70
	v_add_f32_e32 v59, v67, v59
	v_add_f32_e32 v67, v71, v81
	v_add_f32_e32 v16, v67, v16
	v_mul_f32_e32 v67, v81, v81
	v_and_b32_e32 v72, 0xffff0000, v72
	v_and_b32_e32 v76, 0xffff0000, v76
	v_fmac_f32_e32 v67, v71, v71
	v_add_f32_e32 v59, v67, v59
	v_add_f32_e32 v67, v72, v76
	v_add_f32_e32 v16, v67, v16
	v_mul_f32_e32 v67, v76, v76
	v_lshlrev_b32_e32 v78, 16, v73
	v_lshlrev_b32_e32 v82, 16, v77
	v_fmac_f32_e32 v67, v72, v72
	v_add_f32_e32 v59, v67, v59
	v_add_f32_e32 v67, v78, v82
	v_add_f32_e32 v16, v67, v16
	v_mul_f32_e32 v67, v82, v82
	v_and_b32_e32 v73, 0xffff0000, v73
	v_and_b32_e32 v77, 0xffff0000, v77
	v_fmac_f32_e32 v67, v78, v78
	v_add_f32_e32 v59, v67, v59
	v_add_f32_e32 v67, v73, v77
	v_add_f32_e32 v16, v67, v16
	v_mul_f32_e32 v67, v77, v77
	v_fmac_f32_e32 v67, v73, v73
	v_add_f32_dpp v16, v16, v16 quad_perm:[1,0,3,2] row_mask:0xf bank_mask:0xf bound_ctrl:1
	v_add_f32_e32 v59, v67, v59
	s_nop 0
	v_add_f32_dpp v16, v16, v16 quad_perm:[2,3,0,1] row_mask:0xf bank_mask:0xf bound_ctrl:1
	s_nop 1
	v_add_f32_dpp v16, v16, v16 row_half_mirror row_mask:0xf bank_mask:0xf bound_ctrl:1
	s_nop 1
	v_add_f32_dpp v16, v16, v16 row_mirror row_mask:0xf bank_mask:0xf bound_ctrl:1
	s_nop 0
	v_readlane_b32 s9, v16, 0
	v_readlane_b32 s12, v16, 16
	v_readlane_b32 s1, v16, 32
	v_readlane_b32 s11, v16, 48
	v_add_f32_dpp v16, v59, v59 quad_perm:[1,0,3,2] row_mask:0xf bank_mask:0xf bound_ctrl:1
	s_nop 1
	v_add_f32_dpp v16, v16, v16 quad_perm:[2,3,0,1] row_mask:0xf bank_mask:0xf bound_ctrl:1
	s_nop 1
	v_add_f32_dpp v16, v16, v16 row_half_mirror row_mask:0xf bank_mask:0xf bound_ctrl:1
	s_nop 1
	v_add_f32_dpp v16, v16, v16 row_mirror row_mask:0xf bank_mask:0xf bound_ctrl:1
	s_nop 0
	v_readlane_b32 s8, v16, 0
	v_readlane_b32 s14, v16, 16
	v_readlane_b32 s0, v16, 32
	v_readlane_b32 s13, v16, 48
	v_lshl_add_u32 v16, s2, 2, v65
	s_and_saveexec_b64 s[2:3], vcc
	s_cbranch_execz .LBB0_1046
	v_mov_b32_e32 v70, s14
	v_mov_b32_e32 v71, s12
	v_mov_b32_e32 v72, s13
	v_mov_b32_e32 v73, s11
	v_pk_add_f32 v[70:71], s[8:9], v[70:71]
	v_pk_add_f32 v[72:73], s[0:1], v[72:73]
	s_mov_b32 s0, 0x3a800000
	v_pk_add_f32 v[70:71], v[70:71], v[72:73]
	s_nop 0
	v_pk_mul_f32 v[70:71], v[70:71], s[0:1] op_sel_hi:[1,0]
	s_nop 0
	v_fma_f32 v59, -v71, v71, v70
	v_max_f32_e32 v59, 0, v59
	v_add_f32_e32 v59, 0x358637bd, v59
	v_mul_f32_e32 v67, 0x4b800000, v59
	v_cmp_gt_f32_e64 s[0:1], s28, v59
	s_nop 1
	v_cndmask_b32_e64 v59, v59, v67, s[0:1]
	v_rsq_f32_e32 v59, v59
	s_nop 0
	v_mul_f32_e32 v67, 0x45800000, v59
	v_cndmask_b32_e64 v59, v59, v67, s[0:1]
	ds_write2st64_b32 v16, v71, v59 offset1:2

; __device__ __forceinline__ void dprep_unit(const Ctx& c, int l, int b, int chunk, int h) {
;     ...
;     unsigned char* rec = c.ws() + WS_REC + (size_t)((b * 16 + h) * 32 + chunk) * REC_BYTES;
;     const int lane = c.lane, wave = c.wave, m = lane & 15, quad = lane >> 4;
;     const int row0 = b * 2048 + chunk * 64;
;     const bf16* base = c.w<bf16>(WS_QKVB) + (size_t)(b * 2048) * 6144 + h * 128 + 2 * lane;
;     const int t0 = chunk * 64 + 8 * wave;
;     unsigned xq[11], xk[11], xv[11];
; #pragma unroll
;     for (int jr = 0; jr < 11; ++jr) {
;         const int p = t0 - 3 + jr;
;         if (p >= 0) { const bf16* rp = base + (size_t)p * 6144; xq[jr] = *(const unsigned*)rp; xk[jr] = *(const unsigned*)(rp + 2048); xv[jr] = *(const unsigned*)(rp + 4096); }
;         else { xq[jr] = 0u; xk[jr] = 0u; xv[jr] = 0u; }
;     }
;     float wq[4][2], wk[4][2], wv[4][2];
;     const float* cw = c.f(I_CONVW) + (size_t)l * 4 * 6144 + h * 128 + 2 * lane;
; #pragma unroll
;     for (int j = 0; j < 4; ++j) { wq[j][0] = cw[j * 6144]; wq[j][1] = cw[j * 6144 + 1]; wk[j][0] = cw[j * 6144 + 2048]; wk[j][1] = cw[j * 6144 + 2049]; wv[j][0] = cw[j * 6144 + 4096]; wv[j][1] = cw[j * 6144 + 4097]; }
;     if (wave == 0) {
;         const float* AB = c.w<float>(WS_AB) + (size_t)(row0 + lane) * 32;
;         const float xx = AB[h] + c.f(I_DTB)[l * 16 + h];
;         const float sp = xx > 20.f ? xx : log1pf(expf(xx));
;         float G = -expf(c.f(I_ALOG)[l * 16 + h]) * sp;
; #pragma unroll
;         for (int o = 1; o < 64; o <<= 1) { const float t = lane_get(G, lane - o); if (lane >= o) G += t; }
;         Gs[lane] = G; betas[lane] = 1.0f / (1.0f + expf(-AB[16 + h]));
;     }
;     __syncthreads();
;     {
;         const float Gl = Gs[63];
;         unsigned* QGr = (unsigned*)(rec + REC_QG);
; #pragma unroll
;         for (int i = 0; i < 8; ++i) {
;             const int tt = 8 * wave + i;
;             float q0 = 0.f, q1 = 0.f, k0 = 0.f, k1 = 0.f, v0 = 0.f, v1 = 0.f;
; #pragma unroll
;             for (int j = 0; j < 4; ++j) {
;                 q0 += wq[j][0] * bf2f(xq[i + j] & 0xffffu); q1 += wq[j][1] * bf2f(xq[i + j] >> 16);
;                 k0 += wk[j][0] * bf2f(xk[i + j] & 0xffffu); k1 += wk[j][1] * bf2f(xk[i + j] >> 16);
;                 v0 += wv[j][0] * bf2f(xv[i + j] & 0xffffu); v1 += wv[j][1] * bf2f(xv[i + j] >> 16);
;             }
.LBB0_1250:
	v_readlane_b32 s8, v251, 34
	s_waitcnt lgkmcnt(0)
	s_barrier
	v_lshl_add_u32 v173, s8, 2, v169
	s_waitcnt vmcnt(14)
	v_lshlrev_b32_e32 v110, 16, v72
	v_and_b32_e32 v111, 0xffff0000, v72
	s_waitcnt vmcnt(13)
	v_lshlrev_b32_e32 v98, 16, v73
	v_and_b32_e32 v99, 0xffff0000, v73
	ds_read2st64_b32 v[72:73], v173 offset1:1
	ds_read_b32 v63, v169 offset:252
	v_lshlrev_b32_e32 v60, 16, v56
	v_and_b32_e32 v61, 0xffff0000, v56
	v_lshlrev_b32_e32 v54, 16, v57
	v_and_b32_e32 v55, 0xffff0000, v57
	s_waitcnt vmcnt(12)
	v_lshlrev_b32_e32 v56, 16, v71
	v_and_b32_e32 v57, 0xffff0000, v71
	v_lshlrev_b32_e32 v100, 16, v58
	v_and_b32_e32 v101, 0xffff0000, v58
	s_waitcnt vmcnt(3)
	v_pk_fma_f32 v[56:57], v[38:39], v[56:57], 0 op_sel_hi:[1,1,0]
	v_lshlrev_b32_e32 v106, 16, v93
	v_and_b32_e32 v107, 0xffff0000, v93
	s_waitcnt lgkmcnt(1)
	v_mul_f32_e32 v58, 0x3fb8aa3b, v72
	s_waitcnt vmcnt(2)
	v_pk_fma_f32 v[56:57], v[40:41], v[100:101], v[56:57]
	v_lshlrev_b32_e32 v94, 16, v80
	v_and_b32_e32 v95, 0xffff0000, v80
	v_lshlrev_b32_e32 v104, 16, v81
	v_and_b32_e32 v105, 0xffff0000, v81
	v_lshlrev_b32_e32 v80, 16, v97
	v_and_b32_e32 v81, 0xffff0000, v97
	v_lshlrev_b32_e32 v120, 16, v96
	v_and_b32_e32 v121, 0xffff0000, v96
	v_lshlrev_b32_e32 v96, 16, v91
	v_and_b32_e32 v97, 0xffff0000, v91
	v_exp_f32_e32 v116, v58
	s_waitcnt lgkmcnt(0)
	v_sub_f32_e32 v58, v63, v72
	s_waitcnt vmcnt(1)
	v_pk_fma_f32 v[56:57], v[42:43], v[106:107], v[56:57]
	v_mul_f32_e32 v58, 0x3fb8aa3b, v58
	s_waitcnt vmcnt(0)
	v_pk_fma_f32 v[56:57], v[44:45], v[96:97], v[56:57]
	v_exp_f32_e32 v190, v58
	v_mul_f32_e32 v58, 0xbfb8aa3b, v56
	v_exp_f32_e32 v58, v58
	v_mul_f32_e32 v71, 0xbfb8aa3b, v57
	v_exp_f32_e32 v71, v71
	v_pk_fma_f32 v[54:55], v[0:1], v[54:55], 0 op_sel_hi:[1,1,0]
	v_add_f32_e32 v58, 1.0, v58
	v_pk_fma_f32 v[54:55], v[2:3], v[98:99], v[54:55]
	v_rcp_f32_e32 v108, v58
	v_pk_fma_f32 v[54:55], v[4:5], v[104:105], v[54:55]
	v_add_f32_e32 v58, 1.0, v71
	v_pk_fma_f32 v[54:55], v[36:37], v[120:121], v[54:55]
	v_rcp_f32_e32 v109, v58
	v_mul_f32_e32 v58, 0xbfb8aa3b, v54
	s_lshl_b32 s0, s34, 5
	v_exp_f32_e32 v58, v58
	v_mul_f32_e32 v71, 0xbfb8aa3b, v55
	s_or_b32 s0, s0, s39
	v_exp_f32_e32 v71, v71
	s_or_b32 s0, s0, s38
	s_mul_i32 s0, s0, 0x16d00
	s_add_u32 s4, s48, s0
	v_add_f32_e32 v58, 1.0, v58
	s_addc_u32 s5, s49, 0
	v_pk_mul_f32 v[56:57], v[56:57], v[108:109]
	v_rcp_f32_e32 v108, v58
	v_add_f32_e32 v58, 1.0, v71
	s_add_u32 s0, s4, 0x4200
	v_rcp_f32_e32 v109, v58
	v_mov_b32_e32 v128, v73
	s_addc_u32 s1, s5, 0
	v_pk_mul_f32 v[126:127], v[56:57], v[128:129] op_sel_hi:[1,0]
	v_lshlrev_b32_e32 v56, 16, v90
	v_and_b32_e32 v57, 0xffff0000, v90
	v_pk_fma_f32 v[90:91], v[0:1], v[98:99], 0 op_sel_hi:[1,1,0]
	v_lshl_add_u64 v[124:125], v[6:7], 2, s[0:1]
	v_pk_fma_f32 v[6:7], v[38:39], v[100:101], 0 op_sel_hi:[1,1,0]
	v_pk_fma_f32 v[90:91], v[2:3], v[104:105], v[90:91]
	v_pk_fma_f32 v[6:7], v[40:41], v[106:107], v[6:7]
	v_pk_fma_f32 v[90:91], v[4:5], v[120:121], v[90:91]
	v_pk_mul_f32 v[130:131], v[54:55], v[108:109]
	v_lshlrev_b32_e32 v132, 16, v92
	v_and_b32_e32 v133, 0xffff0000, v92
	v_pk_fma_f32 v[6:7], v[42:43], v[96:97], v[6:7]
	v_pk_fma_f32 v[90:91], v[36:37], v[56:57], v[90:91]
	v_pk_mul_f32 v[54:55], v[130:131], v[130:131]
	v_pk_fma_f32 v[6:7], v[44:45], v[132:133], v[6:7]
	v_mul_f32_e32 v58, 0xbfb8aa3b, v90
	v_add_f32_e32 v200, v54, v55
	v_mul_f32_e32 v54, 0xbfb8aa3b, v6
	v_mul_f32_e32 v55, 0xbfb8aa3b, v7
	v_exp_f32_e32 v58, v58
	v_mul_f32_e32 v71, 0xbfb8aa3b, v91
	v_exp_f32_e32 v54, v54
	v_exp_f32_e32 v55, v55
	v_exp_f32_e32 v71, v71
	v_add_f32_e32 v58, 1.0, v58
	v_add_f32_e32 v54, 1.0, v54
	v_add_f32_e32 v55, 1.0, v55
	v_rcp_f32_e32 v92, v58
	v_add_f32_e32 v58, 1.0, v71
	v_rcp_f32_e32 v54, v54
	v_rcp_f32_e32 v55, v55
	v_rcp_f32_e32 v93, v58
	v_lshlrev_b32_e32 v154, 16, v88
	v_and_b32_e32 v155, 0xffff0000, v88
	v_pk_mul_f32 v[122:123], v[6:7], v[54:55]
	v_pk_mul_f32 v[118:119], v[90:91], v[92:93]
	v_pk_fma_f32 v[54:55], v[0:1], v[104:105], 0 op_sel_hi:[1,1,0]
	v_pk_mul_f32 v[6:7], v[118:119], v[118:119]
	v_pk_fma_f32 v[54:55], v[2:3], v[120:121], v[54:55]
	v_add_f32_e32 v201, v6, v7
	v_pk_fma_f32 v[6:7], v[38:39], v[106:107], 0 op_sel_hi:[1,1,0]
	v_pk_fma_f32 v[54:55], v[4:5], v[56:57], v[54:55]
	v_pk_fma_f32 v[6:7], v[40:41], v[96:97], v[6:7]
	v_pk_fma_f32 v[54:55], v[36:37], v[154:155], v[54:55]
	v_lshlrev_b32_e32 v174, 16, v75
	v_and_b32_e32 v175, 0xffff0000, v75
	v_pk_fma_f32 v[6:7], v[42:43], v[132:133], v[6:7]
	v_mul_f32_e32 v58, 0xbfb8aa3b, v54
	v_pk_fma_f32 v[6:7], v[44:45], v[174:175], v[6:7]
	v_exp_f32_e32 v58, v58
	v_mul_f32_e32 v71, 0xbfb8aa3b, v55
	v_lshl_add_u64 v[114:115], v[8:9], 2, s[0:1]
	v_mul_f32_e32 v8, 0xbfb8aa3b, v6
	v_mul_f32_e32 v9, 0xbfb8aa3b, v7
	v_exp_f32_e32 v71, v71
	v_exp_f32_e32 v8, v8
	v_exp_f32_e32 v9, v9
	v_add_f32_e32 v58, 1.0, v58
	v_rcp_f32_e32 v90, v58
	v_add_f32_e32 v58, 1.0, v71
	v_add_f32_e32 v8, 1.0, v8
	v_add_f32_e32 v9, 1.0, v9
	v_rcp_f32_e32 v91, v58
	v_rcp_f32_e32 v8, v8
	v_rcp_f32_e32 v9, v9
	v_lshl_add_u64 v[106:107], v[10:11], 2, s[0:1]
	v_pk_mul_f32 v[108:109], v[54:55], v[90:91]
	v_pk_fma_f32 v[10:11], v[0:1], v[120:121], 0 op_sel_hi:[1,1,0]
	v_pk_mul_f32 v[112:113], v[6:7], v[8:9]
	v_pk_mul_f32 v[6:7], v[108:109], v[108:109]
	v_pk_fma_f32 v[10:11], v[2:3], v[56:57], v[10:11]
	v_add_f32_e32 v188, v6, v7
	v_pk_fma_f32 v[6:7], v[38:39], v[96:97], 0 op_sel_hi:[1,1,0]
	v_lshlrev_b32_e32 v196, 16, v87
	v_and_b32_e32 v197, 0xffff0000, v87
	v_pk_fma_f32 v[6:7], v[40:41], v[132:133], v[6:7]
	v_pk_fma_f32 v[10:11], v[4:5], v[154:155], v[10:11]
	v_lshlrev_b32_e32 v198, 16, v89
	v_and_b32_e32 v199, 0xffff0000, v89
; __device__ __forceinline__ float bf2f(unsigned b) { return __uint_as_float(b << 16); }
; __device__ __forceinline__ float silu_f(float x) { return x * __builtin_amdgcn_rcpf(1.0f + __builtin_amdgcn_exp2f(-1.4426950408889634f * x)); }
; __device__ __forceinline__ float wave_sum(float v) { v = row16_sum(v); return (rlf(v, 0) + rlf(v, 16)) + (rlf(v, 32) + rlf(v, 48)); }
; __device__ __forceinline__ void dprep_unit(const Ctx& c, int l, int b, int chunk, int h) {
;     ...
;     {
;         const float Gl = Gs[63];
;         unsigned* QGr = (unsigned*)(rec + REC_QG);
; #pragma unroll
;         for (int i = 0; i < 8; ++i) {
;             const int tt = 8 * wave + i;
;             float q0 = 0.f, q1 = 0.f, k0 = 0.f, k1 = 0.f, v0 = 0.f, v1 = 0.f;
; #pragma unroll
;             for (int j = 0; j < 4; ++j) {
;                 q0 += wq[j][0] * bf2f(xq[i + j] & 0xffffu); q1 += wq[j][1] * bf2f(xq[i + j] >> 16);
;                 k0 += wk[j][0] * bf2f(xk[i + j] & 0xffffu); k1 += wk[j][1] * bf2f(xk[i + j] >> 16);
;                 v0 += wv[j][0] * bf2f(xv[i + j] & 0xffffu); v1 += wv[j][1] * bf2f(xv[i + j] >> 16);
;             }
;             q0 = silu_f(q0); q1 = silu_f(q1); k0 = silu_f(k0); k1 = silu_f(k1); v0 = silu_f(v0); v1 = silu_f(v1);
;             const float rq = rsqrtf(wave_sum(q0 * q0 + q1 * q1) + 1e-6f), rk = rsqrtf(wave_sum(k0 * k0 + k1 * k1) + 1e-6f);
;             q0 *= rq; q1 *= rq; k0 *= rk; k1 *= rk;
	v_pk_fma_f32 v[6:7], v[42:43], v[174:175], v[6:7]
	v_pk_fma_f32 v[10:11], v[36:37], v[196:197], v[10:11]
	v_pk_fma_f32 v[6:7], v[44:45], v[198:199], v[6:7]
	v_mul_f32_e32 v54, 0xbfb8aa3b, v10
	v_mul_f32_e32 v55, 0xbfb8aa3b, v11
	v_mul_f32_e32 v8, 0xbfb8aa3b, v6
	v_mul_f32_e32 v9, 0xbfb8aa3b, v7
	v_exp_f32_e32 v54, v54
	v_exp_f32_e32 v55, v55
	v_exp_f32_e32 v8, v8
	v_exp_f32_e32 v9, v9
	v_add_f32_e32 v54, 1.0, v54
	v_add_f32_e32 v55, 1.0, v55
	v_add_f32_e32 v8, 1.0, v8
	v_add_f32_e32 v9, 1.0, v9
	v_rcp_f32_e32 v54, v54
	v_rcp_f32_e32 v55, v55
	v_rcp_f32_e32 v8, v8
	v_rcp_f32_e32 v9, v9
	v_pk_fma_f32 v[56:57], v[0:1], v[56:57], 0 op_sel_hi:[1,1,0]
	v_pk_mul_f32 v[100:101], v[10:11], v[54:55]
	v_pk_fma_f32 v[10:11], v[38:39], v[132:133], 0 op_sel_hi:[1,1,0]
	v_pk_mul_f32 v[104:105], v[6:7], v[8:9]
	v_pk_mul_f32 v[6:7], v[100:101], v[100:101]
	v_pk_fma_f32 v[56:57], v[2:3], v[154:155], v[56:57]
	v_add_f32_e32 v184, v6, v7
	v_lshlrev_b32_e32 v6, 16, v84
	v_and_b32_e32 v7, 0xffff0000, v84
	v_pk_fma_f32 v[10:11], v[40:41], v[174:175], v[10:11]
	v_pk_fma_f32 v[56:57], v[4:5], v[196:197], v[56:57]
	v_lshlrev_b32_e32 v8, 16, v59
	v_and_b32_e32 v9, 0xffff0000, v59
	v_pk_fma_f32 v[10:11], v[42:43], v[198:199], v[10:11]
	v_pk_fma_f32 v[56:57], v[36:37], v[6:7], v[56:57]
	v_pk_fma_f32 v[10:11], v[44:45], v[8:9], v[10:11]
	v_mul_f32_e32 v58, 0xbfb8aa3b, v56
	v_mul_f32_e32 v59, 0xbfb8aa3b, v57
	v_lshl_add_u64 v[98:99], v[12:13], 2, s[0:1]
	v_mul_f32_e32 v12, 0xbfb8aa3b, v10
	v_mul_f32_e32 v13, 0xbfb8aa3b, v11
	v_exp_f32_e32 v58, v58
	v_exp_f32_e32 v59, v59
	v_exp_f32_e32 v12, v12
	v_exp_f32_e32 v13, v13
	v_add_f32_e32 v58, 1.0, v58
	v_add_f32_e32 v59, 1.0, v59
	v_add_f32_e32 v12, 1.0, v12
	v_add_f32_e32 v13, 1.0, v13
	v_rcp_f32_e32 v58, v58
	v_rcp_f32_e32 v59, v59
	v_rcp_f32_e32 v12, v12
	v_rcp_f32_e32 v13, v13
	v_lshlrev_b32_e32 v90, 16, v85
	v_pk_mul_f32 v[92:93], v[56:57], v[58:59]
	v_lshlrev_b32_e32 v56, 16, v74
	v_and_b32_e32 v57, 0xffff0000, v74
	v_pk_fma_f32 v[74:75], v[0:1], v[154:155], 0 op_sel_hi:[1,1,0]
	v_pk_mul_f32 v[96:97], v[10:11], v[12:13]
	v_pk_mul_f32 v[10:11], v[92:93], v[92:93]
	v_pk_fma_f32 v[74:75], v[2:3], v[196:197], v[74:75]
	v_and_b32_e32 v91, 0xffff0000, v85
	v_add_f32_e32 v180, v10, v11
	v_lshl_add_u64 v[84:85], v[14:15], 2, s[0:1]
	v_lshlrev_b32_e32 v10, 16, v78
	v_and_b32_e32 v11, 0xffff0000, v78
	v_pk_fma_f32 v[14:15], v[38:39], v[174:175], 0 op_sel_hi:[1,1,0]
	v_pk_fma_f32 v[74:75], v[4:5], v[6:7], v[74:75]
	v_pk_fma_f32 v[14:15], v[40:41], v[198:199], v[14:15]
	v_pk_fma_f32 v[74:75], v[36:37], v[10:11], v[74:75]
	v_lshlrev_b32_e32 v12, 16, v86
	v_and_b32_e32 v13, 0xffff0000, v86
	v_pk_fma_f32 v[14:15], v[42:43], v[8:9], v[14:15]
	v_mul_f32_e32 v71, 0xbfb8aa3b, v74
	v_pk_fma_f32 v[14:15], v[44:45], v[12:13], v[14:15]
	v_exp_f32_e32 v71, v71
	v_mul_f32_e32 v78, 0xbfb8aa3b, v75
	v_lshlrev_b32_e32 v54, 16, v79
	v_and_b32_e32 v55, 0xffff0000, v79
	v_mul_f32_e32 v58, 0xbfb8aa3b, v14
	v_mul_f32_e32 v59, 0xbfb8aa3b, v15
	v_exp_f32_e32 v79, v78
	v_exp_f32_e32 v58, v58
	v_exp_f32_e32 v59, v59
	v_add_f32_e32 v71, 1.0, v71
	v_rcp_f32_e32 v78, v71
	v_add_f32_e32 v71, 1.0, v79
	v_add_f32_e32 v58, 1.0, v58
	v_add_f32_e32 v59, 1.0, v59
	v_rcp_f32_e32 v79, v71
	v_rcp_f32_e32 v58, v58
	v_rcp_f32_e32 v59, v59
	v_pk_fma_f32 v[60:61], v[46:47], v[60:61], 0 op_sel_hi:[1,1,0]
	v_pk_mul_f32 v[88:89], v[74:75], v[78:79]
	v_pk_fma_f32 v[78:79], v[0:1], v[196:197], 0 op_sel_hi:[1,1,0]
	v_pk_mul_f32 v[86:87], v[14:15], v[58:59]
	v_pk_mul_f32 v[14:15], v[88:89], v[88:89]
	v_pk_fma_f32 v[78:79], v[2:3], v[6:7], v[78:79]
	v_add_f32_e32 v177, v14, v15
	v_lshl_add_u64 v[74:75], v[18:19], 2, s[0:1]
	v_lshlrev_b32_e32 v14, 16, v77
	v_and_b32_e32 v15, 0xffff0000, v77
	v_lshlrev_b32_e32 v18, 16, v70
	v_and_b32_e32 v19, 0xffff0000, v70
	v_pk_fma_f32 v[70:71], v[38:39], v[198:199], 0 op_sel_hi:[1,1,0]
	v_pk_fma_f32 v[78:79], v[4:5], v[10:11], v[78:79]
	v_pk_fma_f32 v[70:71], v[40:41], v[8:9], v[70:71]
	v_pk_fma_f32 v[78:79], v[36:37], v[14:15], v[78:79]
	v_pk_fma_f32 v[70:71], v[42:43], v[12:13], v[70:71]
	v_mul_f32_e32 v103, 0xbfb8aa3b, v78
	v_pk_fma_f32 v[70:71], v[44:45], v[18:19], v[70:71]
	v_exp_f32_e32 v103, v103
	v_mul_f32_e32 v120, 0xbfb8aa3b, v79
	v_lshlrev_b32_e32 v58, 16, v76
	v_and_b32_e32 v59, 0xffff0000, v76
	v_mul_f32_e32 v76, 0xbfb8aa3b, v70
	v_mul_f32_e32 v77, 0xbfb8aa3b, v71
	v_exp_f32_e32 v121, v120
	v_exp_f32_e32 v76, v76
	v_exp_f32_e32 v77, v77
	v_add_f32_e32 v103, 1.0, v103
	v_rcp_f32_e32 v120, v103
	v_add_f32_e32 v103, 1.0, v121
	v_add_f32_e32 v76, 1.0, v76
	v_add_f32_e32 v77, 1.0, v77
	v_rcp_f32_e32 v121, v103
	v_rcp_f32_e32 v76, v76
	v_rcp_f32_e32 v77, v77
	v_pk_fma_f32 v[60:61], v[48:49], v[110:111], v[60:61]
	v_pk_mul_f32 v[78:79], v[78:79], v[120:121]
	v_pk_fma_f32 v[60:61], v[50:51], v[94:95], v[60:61]
	v_pk_mul_f32 v[76:77], v[70:71], v[76:77]
	v_pk_mul_f32 v[70:71], v[78:79], v[78:79]
	v_add_u32_e32 v176, v172, v148
	v_add_u32_e32 v178, v171, v148
	v_add_f32_e32 v148, v70, v71
	v_lshlrev_b32_e32 v70, 16, v102
	v_and_b32_e32 v71, 0xffff0000, v102
	v_pk_fma_f32 v[102:103], v[52:53], v[80:81], v[60:61]
	v_readlane_b32 s8, v251, 22
	v_mul_f32_e32 v60, 0xbfb8aa3b, v102
	v_exp_f32_e32 v61, v60
	v_mul_f32_e32 v60, 0xbfb8aa3b, v103
	v_exp_f32_e32 v121, v60
	v_add3_u32 v195, v144, s8, v141
	v_add_f32_e32 v61, 1.0, v61
	v_rcp_f32_e32 v120, v61
	v_add_f32_e32 v61, 1.0, v121
	v_rcp_f32_e32 v121, v61
	v_readlane_b32 s8, v251, 23
	v_add_u32_e32 v174, v172, v150
	v_add_u32_e32 v175, v171, v150
	v_pk_mul_f32 v[132:133], v[102:103], v[120:121]
	v_add3_u32 v192, v144, s8, v141
	v_pk_mul_f32 v[102:103], v[132:133], v[132:133]
	v_readlane_b32 s8, v251, 25
; __device__ __forceinline__ unsigned cvt_pk_bf16(float lo, float hi) { unsigned r; asm volatile("v_cvt_pk_bf16_f32 %0, %1, %2" : "=v"(r) : "v"(lo), "v"(hi)); return r; }
; #define LAS __attribute__((address_space(3)))
; __device__ __forceinline__ float bf2f(unsigned b) { return __uint_as_float(b << 16); }
; __device__ __forceinline__ unsigned f2bf(float f) { unsigned u = __float_as_uint(f); u += 0x7FFFu + ((u >> 16) & 1u); return u >> 16; }
; __device__ __forceinline__ float silu_f(float x) { return x * __builtin_amdgcn_rcpf(1.0f + __builtin_amdgcn_exp2f(-1.4426950408889634f * x)); }
; __device__ __forceinline__ void dprep_unit(const Ctx& c, int l, int b, int chunk, int h) {
;     ...
;         for (int i = 0; i < 8; ++i) {
;             const int tt = 8 * wave + i;
;             float q0 = 0.f, q1 = 0.f, k0 = 0.f, k1 = 0.f, v0 = 0.f, v1 = 0.f;
; #pragma unroll
;             for (int j = 0; j < 4; ++j) {
;                 q0 += wq[j][0] * bf2f(xq[i + j] & 0xffffu); q1 += wq[j][1] * bf2f(xq[i + j] >> 16);
;                 k0 += wk[j][0] * bf2f(xk[i + j] & 0xffffu); k1 += wk[j][1] * bf2f(xk[i + j] >> 16);
;                 v0 += wv[j][0] * bf2f(xv[i + j] & 0xffffu); v1 += wv[j][1] * bf2f(xv[i + j] >> 16);
;             }
;             q0 = silu_f(q0); q1 = silu_f(q1); k0 = silu_f(k0); k1 = silu_f(k1); v0 = silu_f(v0); v1 = silu_f(v1);
;             const float rq = rsqrtf(wave_sum(q0 * q0 + q1 * q1) + 1e-6f), rk = rsqrtf(wave_sum(k0 * k0 + k1 * k1) + 1e-6f);
;             q0 *= rq; q1 *= rq; k0 *= rk; k1 *= rk;
;             const float G = Gs[tt], be = betas[tt], eG = __expf(G), eGl = __expf(Gl - G);
;             ((LAS unsigned*)qs)[tt * 72 + lane] = pg8::cvt_pk_bf16(q0, q1);
;             ((LAS unsigned*)ks)[tt * 72 + lane] = pg8::cvt_pk_bf16(k0, k1);
;             *(LAS f32x2*)(rhs + tt * 256 + 2 * lane) = (f32x2){v0 * be, v1 * be};
;             *(LAS f32x2*)(rhs + tt * 256 + 128 + 2 * lane) = (f32x2){k0 * be * eG, k1 * be * eG};
;             ((LAS bf16*)kgT)[(2 * lane) * (REC_PK / 2) + tt] = (bf16)f2bf(k0 * eGl);
;             ((LAS bf16*)kgT)[(2 * lane + 1) * (REC_PK / 2) + tt] = (bf16)f2bf(k1 * eGl);
;             const float sq = 0.08838834764831845f * eG;
;             QGr[tt * (REC_PW / 4) + lane] = pg8::cvt_pk_bf16(q0 * sq, q1 * sq);
;         }
	v_add_f32_e32 v102, v102, v103
	v_add_u32_e32 v189, v172, v146
	v_add3_u32 v187, v144, s8, v141
	v_add_f32_dpp v102, v102, v102 quad_perm:[1,0,3,2] row_mask:0xf bank_mask:0xf bound_ctrl:1
	v_readlane_b32 s8, v251, 27
	v_add_u32_e32 v191, v171, v146
	v_add_f32_dpp v102, v102, v102 quad_perm:[2,3,0,1] row_mask:0xf bank_mask:0xf bound_ctrl:1
	v_add3_u32 v183, v144, s8, v141
	v_readlane_b32 s8, v251, 29
	v_add_f32_dpp v102, v102, v102 row_half_mirror row_mask:0xf bank_mask:0xf bound_ctrl:1
	v_add_u32_e32 v181, v172, v145
	v_add3_u32 v179, v144, s8, v141
	v_readlane_b32 s8, v251, 31
	v_add_f32_dpp v102, v102, v102 row_mirror row_mask:0xf bank_mask:0xf bound_ctrl:1
	v_add_u32_e32 v182, v171, v145
	v_add3_u32 v150, v144, s8, v141
	v_readlane_b32 s8, v251, 33
	v_readlane_b32 s10, v102, 16
	v_readlane_b32 s11, v102, 48
	v_add3_u32 v146, v144, s8, v141
	v_readlane_b32 s8, v102, 0
	v_readlane_b32 s9, v102, 32
	v_mov_b32_e32 v102, s10
	v_mov_b32_e32 v103, s11
	v_pk_add_f32 v[102:103], s[8:9], v[102:103]
	v_add_u32_e32 v145, v172, v151
	v_add_f32_e32 v102, v102, v103
	v_add_f32_e32 v102, 0x358637bd, v102
	v_mul_f32_e32 v103, 0x4b800000, v102
	v_cmp_gt_f32_e32 vcc, s28, v102
	v_add_u32_e32 v147, v171, v151
	v_add_u32_e32 v193, v172, v149
	v_cndmask_b32_e32 v102, v102, v103, vcc
	v_rsq_f32_e32 v151, v102
	v_add_u32_e32 v194, v171, v149
	v_add3_u32 v149, v170, v137, s50
	v_mul_f32_e32 v137, 0x3db504f3, v116
	v_mul_f32_e32 v154, 0x45800000, v151
	v_cndmask_b32_e32 v151, v151, v154, vcc
	v_mul_f32_e32 v196, v132, v151
	v_add_f32_dpp v132, v200, v200 quad_perm:[1,0,3,2] row_mask:0xf bank_mask:0xf bound_ctrl:1
	v_mul_f32_e32 v151, v133, v151
	v_cvt_pk_bf16_f32 v133, v196, v151
	ds_write_b32 v193, v133
	v_add_f32_dpp v132, v132, v132 quad_perm:[2,3,0,1] row_mask:0xf bank_mask:0xf bound_ctrl:1
	v_pk_fma_f32 v[110:111], v[46:47], v[110:111], 0 op_sel_hi:[1,1,0]
	v_lshlrev_b32_e32 v72, 16, v82
	v_add_f32_dpp v132, v132, v132 row_half_mirror row_mask:0xf bank_mask:0xf bound_ctrl:1
	v_pk_fma_f32 v[110:111], v[48:49], v[94:95], v[110:111]
	v_and_b32_e32 v73, 0xffff0000, v82
	v_add_f32_dpp v132, v132, v132 row_mirror row_mask:0xf bank_mask:0xf bound_ctrl:1
	v_pk_fma_f32 v[110:111], v[50:51], v[80:81], v[110:111]
	v_readlane_b32 s10, v132, 16
	v_readlane_b32 s11, v132, 48
	v_readlane_b32 s8, v132, 0
	v_readlane_b32 s9, v132, 32
	v_mov_b32_e32 v154, s10
	v_mov_b32_e32 v155, s11
	v_pk_add_f32 v[154:155], s[8:9], v[154:155]
	v_pk_fma_f32 v[110:111], v[52:53], v[72:73], v[110:111]
	v_add_f32_e32 v132, v154, v155
	v_add_f32_e32 v132, 0x358637bd, v132
	v_mul_f32_e32 v154, 0x4b800000, v132
	v_cmp_gt_f32_e32 vcc, s28, v132
	v_pk_fma_f32 v[94:95], v[46:47], v[94:95], 0 op_sel_hi:[1,1,0]
	v_lshlrev_b32_e32 v82, 16, v83
	v_cndmask_b32_e32 v132, v132, v154, vcc
	v_rsq_f32_e32 v132, v132
	v_pk_fma_f32 v[94:95], v[48:49], v[80:81], v[94:95]
	v_and_b32_e32 v83, 0xffff0000, v83
	v_pk_fma_f32 v[94:95], v[50:51], v[72:73], v[94:95]
	v_mul_f32_e32 v133, 0x45800000, v132
	v_cndmask_b32_e32 v132, v132, v133, vcc
	v_pk_mul_f32 v[130:131], v[130:131], v[132:133] op_sel_hi:[1,0]
	v_pk_fma_f32 v[94:95], v[52:53], v[82:83], v[94:95]
	v_cvt_pk_bf16_f32 v132, v130, v131
	ds_write_b32 v194, v132
	v_pk_mul_f32 v[132:133], v[128:129], v[130:131] op_sel_hi:[0,1]
	v_pk_mul_f32 v[132:133], v[116:117], v[132:133] op_sel_hi:[0,1]
	v_mul_f32_e32 v116, v190, v130
	ds_write2st64_b64 v195, v[126:127], v[132:133] offset1:1
	v_bfe_u32 v126, v116, 16, 1
	v_add3_u32 v116, v116, v126, s33
	ds_write_b16_d16_hi v149, v116
	v_mul_f32_e32 v116, v190, v131
	v_bfe_u32 v126, v116, 16, 1
	v_add3_u32 v116, v116, v126, s33
	ds_write_b16_d16_hi v149, v116 offset:136
	v_mul_f32_e32 v116, v196, v137
	v_mul_f32_e32 v126, v151, v137
	v_cvt_pk_bf16_f32 v116, v116, v126
	global_store_dword v[124:125], v116, off
	v_mul_f32_e32 v124, 0xbfb8aa3b, v110
	v_mul_f32_e32 v125, 0xbfb8aa3b, v111
	v_exp_f32_e32 v124, v124
	v_exp_f32_e32 v125, v125
	ds_read2_b32 v[126:127], v173 offset0:1 offset1:65
	v_add_u32_e32 v185, v172, v62
	v_add_f32_e32 v124, 1.0, v124
	v_add_f32_e32 v125, 1.0, v125
	v_rcp_f32_e32 v124, v124
	v_rcp_f32_e32 v125, v125
	s_waitcnt lgkmcnt(0)
	v_mul_f32_e32 v116, 0x3fb8aa3b, v126
	v_sub_f32_e32 v126, v63, v126
	v_mul_f32_e32 v126, 0x3fb8aa3b, v126
	v_pk_mul_f32 v[110:111], v[110:111], v[124:125]
	v_exp_f32_e32 v128, v126
	v_pk_mul_f32 v[124:125], v[110:111], v[110:111]
	v_exp_f32_e32 v116, v116
	v_add_f32_e32 v124, v124, v125
	v_add_u32_e32 v186, v171, v62
	v_pk_fma_f32 v[80:81], v[46:47], v[80:81], 0 op_sel_hi:[1,1,0]
	v_add_f32_dpp v124, v124, v124 quad_perm:[1,0,3,2] row_mask:0xf bank_mask:0xf bound_ctrl:1
	v_mul_f32_e32 v130, 0x3db504f3, v116
	v_pk_fma_f32 v[80:81], v[48:49], v[72:73], v[80:81]
	v_add_f32_dpp v124, v124, v124 quad_perm:[2,3,0,1] row_mask:0xf bank_mask:0xf bound_ctrl:1
	v_pk_fma_f32 v[80:81], v[50:51], v[82:83], v[80:81]
	v_pk_fma_f32 v[72:73], v[46:47], v[72:73], 0 op_sel_hi:[1,1,0]
	v_add_f32_dpp v124, v124, v124 row_half_mirror row_mask:0xf bank_mask:0xf bound_ctrl:1
	v_pk_fma_f32 v[80:81], v[52:53], v[90:91], v[80:81]
	v_pk_fma_f32 v[72:73], v[48:49], v[82:83], v[72:73]
	v_add_f32_dpp v124, v124, v124 row_mirror row_mask:0xf bank_mask:0xf bound_ctrl:1
	v_pk_fma_f32 v[72:73], v[50:51], v[90:91], v[72:73]
	v_readlane_b32 s10, v124, 16
	v_readlane_b32 s11, v124, 48
	v_readlane_b32 s8, v124, 0
	v_readlane_b32 s9, v124, 32
	v_mov_b32_e32 v124, s10
	v_mov_b32_e32 v125, s11
	v_pk_add_f32 v[124:125], s[8:9], v[124:125]
	v_pk_fma_f32 v[72:73], v[52:53], v[54:55], v[72:73]
	v_add_f32_e32 v124, v124, v125
	v_add_f32_e32 v124, 0x358637bd, v124
	v_mul_f32_e32 v125, 0x4b800000, v124
	v_cmp_gt_f32_e32 vcc, s28, v124
; __device__ __forceinline__ unsigned cvt_pk_bf16(float lo, float hi) { unsigned r; asm volatile("v_cvt_pk_bf16_f32 %0, %1, %2" : "=v"(r) : "v"(lo), "v"(hi)); return r; }
; #define LAS __attribute__((address_space(3)))
; __device__ __forceinline__ float bf2f(unsigned b) { return __uint_as_float(b << 16); }
; __device__ __forceinline__ unsigned f2bf(float f) { unsigned u = __float_as_uint(f); u += 0x7FFFu + ((u >> 16) & 1u); return u >> 16; }
; __device__ __forceinline__ float silu_f(float x) { return x * __builtin_amdgcn_rcpf(1.0f + __builtin_amdgcn_exp2f(-1.4426950408889634f * x)); }
; __device__ __forceinline__ void dprep_unit(const Ctx& c, int l, int b, int chunk, int h) {
;     ...
;         for (int i = 0; i < 8; ++i) {
;             const int tt = 8 * wave + i;
;             float q0 = 0.f, q1 = 0.f, k0 = 0.f, k1 = 0.f, v0 = 0.f, v1 = 0.f;
; #pragma unroll
;             for (int j = 0; j < 4; ++j) {
;                 q0 += wq[j][0] * bf2f(xq[i + j] & 0xffffu); q1 += wq[j][1] * bf2f(xq[i + j] >> 16);
;                 k0 += wk[j][0] * bf2f(xk[i + j] & 0xffffu); k1 += wk[j][1] * bf2f(xk[i + j] >> 16);
;                 v0 += wv[j][0] * bf2f(xv[i + j] & 0xffffu); v1 += wv[j][1] * bf2f(xv[i + j] >> 16);
;             }
;             q0 = silu_f(q0); q1 = silu_f(q1); k0 = silu_f(k0); k1 = silu_f(k1); v0 = silu_f(v0); v1 = silu_f(v1);
;             const float rq = rsqrtf(wave_sum(q0 * q0 + q1 * q1) + 1e-6f), rk = rsqrtf(wave_sum(k0 * k0 + k1 * k1) + 1e-6f);
;             q0 *= rq; q1 *= rq; k0 *= rk; k1 *= rk;
;             const float G = Gs[tt], be = betas[tt], eG = __expf(G), eGl = __expf(Gl - G);
;             ((LAS unsigned*)qs)[tt * 72 + lane] = pg8::cvt_pk_bf16(q0, q1);
;             ((LAS unsigned*)ks)[tt * 72 + lane] = pg8::cvt_pk_bf16(k0, k1);
;             *(LAS f32x2*)(rhs + tt * 256 + 2 * lane) = (f32x2){v0 * be, v1 * be};
;             *(LAS f32x2*)(rhs + tt * 256 + 128 + 2 * lane) = (f32x2){k0 * be * eG, k1 * be * eG};
;             ((LAS bf16*)kgT)[(2 * lane) * (REC_PK / 2) + tt] = (bf16)f2bf(k0 * eGl);
;             ((LAS bf16*)kgT)[(2 * lane + 1) * (REC_PK / 2) + tt] = (bf16)f2bf(k1 * eGl);
;             const float sq = 0.08838834764831845f * eG;
;             QGr[tt * (REC_PW / 4) + lane] = pg8::cvt_pk_bf16(q0 * sq, q1 * sq);
;         }
	v_pk_fma_f32 v[120:121], v[46:47], v[82:83], 0 op_sel_hi:[1,1,0]
	v_mul_f32_e32 v83, 0xbfb8aa3b, v72
	v_cndmask_b32_e32 v124, v124, v125, vcc
	v_rsq_f32_e32 v125, v124
	v_mov_b32_e32 v124, v127
	v_pk_fma_f32 v[102:103], v[46:47], v[90:91], 0 op_sel_hi:[1,1,0]
	v_pk_fma_f32 v[120:121], v[48:49], v[90:91], v[120:121]
	v_mul_f32_e32 v126, 0x45800000, v125
	v_pk_mul_f32 v[122:123], v[122:123], v[124:125] op_sel_hi:[1,0]
	v_cndmask_b32_e32 v125, v125, v126, vcc
	v_mul_f32_e32 v131, v110, v125
	v_add_f32_dpp v110, v201, v201 quad_perm:[1,0,3,2] row_mask:0xf bank_mask:0xf bound_ctrl:1
	v_mul_f32_e32 v125, v111, v125
	v_cvt_pk_bf16_f32 v111, v131, v125
	ds_write_b32 v189, v111
	v_add_f32_dpp v110, v110, v110 quad_perm:[2,3,0,1] row_mask:0xf bank_mask:0xf bound_ctrl:1
	v_exp_f32_e32 v83, v83
	v_mul_f32_e32 v90, 0xbfb8aa3b, v73
	v_add_f32_dpp v110, v110, v110 row_half_mirror row_mask:0xf bank_mask:0xf bound_ctrl:1
	v_exp_f32_e32 v91, v90
	v_add_f32_e32 v83, 1.0, v83
	v_add_f32_dpp v110, v110, v110 row_mirror row_mask:0xf bank_mask:0xf bound_ctrl:1
	v_rcp_f32_e32 v90, v83
	v_readlane_b32 s10, v110, 16
	v_readlane_b32 s11, v110, 48
	v_readlane_b32 s8, v110, 0
	v_readlane_b32 s9, v110, 32
	v_mov_b32_e32 v126, s10
	v_mov_b32_e32 v127, s11
	v_pk_add_f32 v[126:127], s[8:9], v[126:127]
	v_add_f32_e32 v83, 1.0, v91
	v_add_f32_e32 v110, v126, v127
	v_add_f32_e32 v110, 0x358637bd, v110
	v_mul_f32_e32 v126, 0x4b800000, v110
	v_cmp_gt_f32_e32 vcc, s28, v110
	v_rcp_f32_e32 v91, v83
	v_pk_fma_f32 v[46:47], v[46:47], v[54:55], 0 op_sel_hi:[1,1,0]
	v_cndmask_b32_e32 v110, v110, v126, vcc
	v_rsq_f32_e32 v110, v110
	v_pk_mul_f32 v[72:73], v[72:73], v[90:91]
	v_pk_fma_f32 v[46:47], v[48:49], v[56:57], v[46:47]
	v_pk_mul_f32 v[90:91], v[72:73], v[72:73]
	v_mul_f32_e32 v111, 0x45800000, v110
	v_cndmask_b32_e32 v110, v110, v111, vcc
	v_pk_mul_f32 v[110:111], v[118:119], v[110:111] op_sel_hi:[1,0]
	v_pk_fma_f32 v[46:47], v[50:51], v[58:59], v[46:47]
	v_cvt_pk_bf16_f32 v118, v110, v111
	ds_write_b32 v191, v118
	v_pk_mul_f32 v[118:119], v[124:125], v[110:111] op_sel_hi:[0,1]
	v_mul_f32_e32 v110, v128, v110
	v_pk_mul_f32 v[118:119], v[116:117], v[118:119] op_sel_hi:[0,1]
	v_bfe_u32 v116, v110, 16, 1
	v_add3_u32 v110, v110, v116, s33
	ds_write2st64_b64 v192, v[122:123], v[118:119] offset1:1
	ds_write_b16_d16_hi v149, v110 offset:2
	v_mul_f32_e32 v110, v128, v111
	v_bfe_u32 v111, v110, 16, 1
	v_add3_u32 v110, v110, v111, s33
	ds_write_b16_d16_hi v149, v110 offset:138
	v_mul_f32_e32 v110, v131, v130
	v_mul_f32_e32 v111, v125, v130
	v_cvt_pk_bf16_f32 v116, v110, v111
	global_store_dword v[114:115], v116, off
	v_mul_f32_e32 v115, 0xbfb8aa3b, v94
	v_exp_f32_e32 v115, v115
	v_mul_f32_e32 v116, 0xbfb8aa3b, v95
	v_exp_f32_e32 v116, v116
	ds_read2_b32 v[110:111], v173 offset0:2 offset1:66
	v_add_f32_e32 v115, 1.0, v115
	v_rcp_f32_e32 v118, v115
	v_add_f32_e32 v115, 1.0, v116
	v_rcp_f32_e32 v119, v115
	s_waitcnt lgkmcnt(0)
	v_mul_f32_e32 v114, 0x3fb8aa3b, v110
	v_sub_f32_e32 v110, v63, v110
	v_mul_f32_e32 v110, 0x3fb8aa3b, v110
	v_pk_mul_f32 v[94:95], v[94:95], v[118:119]
	v_exp_f32_e32 v115, v110
	v_pk_mul_f32 v[118:119], v[94:95], v[94:95]
	v_exp_f32_e32 v114, v114
	v_add_f32_e32 v110, v118, v119
	v_pk_fma_f32 v[46:47], v[52:53], v[70:71], v[46:47]
	v_pk_fma_f32 v[0:1], v[0:1], v[6:7], 0 op_sel_hi:[1,1,0]
	v_add_f32_dpp v110, v110, v110 quad_perm:[1,0,3,2] row_mask:0xf bank_mask:0xf bound_ctrl:1
	v_pk_fma_f32 v[0:1], v[2:3], v[10:11], v[0:1]
	v_lshlrev_b32_e32 v60, 16, v68
	v_add_f32_dpp v110, v110, v110 quad_perm:[2,3,0,1] row_mask:0xf bank_mask:0xf bound_ctrl:1
	v_and_b32_e32 v61, 0xffff0000, v68
	v_pk_fma_f32 v[0:1], v[4:5], v[14:15], v[0:1]
	v_add_f32_dpp v110, v110, v110 row_half_mirror row_mask:0xf bank_mask:0xf bound_ctrl:1
	v_pk_fma_f32 v[0:1], v[36:37], v[60:61], v[0:1]
	v_pk_fma_f32 v[8:9], v[38:39], v[8:9], 0 op_sel_hi:[1,1,0]
	v_add_f32_dpp v110, v110, v110 row_mirror row_mask:0xf bank_mask:0xf bound_ctrl:1
	v_mul_f32_e32 v2, 0xbfb8aa3b, v0
	v_readlane_b32 s10, v110, 16
	v_readlane_b32 s11, v110, 48
	v_readlane_b32 s8, v110, 0
	v_readlane_b32 s9, v110, 32
	v_mov_b32_e32 v118, s10
	v_mov_b32_e32 v119, s11
	v_pk_add_f32 v[118:119], s[8:9], v[118:119]
	v_mul_f32_e32 v3, 0xbfb8aa3b, v1
	v_add_f32_e32 v110, v118, v119
	v_add_f32_e32 v110, 0x358637bd, v110
	v_mul_f32_e32 v116, 0x4b800000, v110
	v_cmp_gt_f32_e32 vcc, s28, v110
	v_exp_f32_e32 v2, v2
	v_exp_f32_e32 v3, v3
	v_cndmask_b32_e32 v110, v110, v116, vcc
	v_rsq_f32_e32 v116, v110
	v_mov_b32_e32 v110, v111
	v_pk_mul_f32 v[112:113], v[112:113], v[110:111] op_sel_hi:[1,0]
	v_mul_f32_e32 v111, 0x3db504f3, v114
	v_mul_f32_e32 v118, 0x45800000, v116
	v_cndmask_b32_e32 v116, v116, v118, vcc
	v_mul_f32_e32 v122, v94, v116
	v_add_f32_dpp v94, v188, v188 quad_perm:[1,0,3,2] row_mask:0xf bank_mask:0xf bound_ctrl:1
	v_mul_f32_e32 v116, v95, v116
	v_cvt_pk_bf16_f32 v95, v122, v116
	ds_write_b32 v185, v95
	v_add_f32_dpp v94, v94, v94 quad_perm:[2,3,0,1] row_mask:0xf bank_mask:0xf bound_ctrl:1
	v_add_f32_e32 v2, 1.0, v2
	v_add_f32_e32 v3, 1.0, v3
	v_add_f32_dpp v94, v94, v94 row_half_mirror row_mask:0xf bank_mask:0xf bound_ctrl:1
	v_rcp_f32_e32 v2, v2
	v_rcp_f32_e32 v3, v3
	v_add_f32_dpp v94, v94, v94 row_mirror row_mask:0xf bank_mask:0xf bound_ctrl:1
	v_pk_fma_f32 v[8:9], v[40:41], v[12:13], v[8:9]
	v_readlane_b32 s10, v94, 16
	v_readlane_b32 s11, v94, 48
	v_readlane_b32 s8, v94, 0
	v_readlane_b32 s9, v94, 32
	v_mov_b32_e32 v118, s10
	v_mov_b32_e32 v119, s11
	v_pk_add_f32 v[118:119], s[8:9], v[118:119]
	v_pk_mul_f32 v[0:1], v[0:1], v[2:3]
	v_add_f32_e32 v94, v118, v119
	v_add_f32_e32 v94, 0x358637bd, v94
	v_mul_f32_e32 v118, 0x4b800000, v94
; __device__ __forceinline__ unsigned cvt_pk_bf16(float lo, float hi) { unsigned r; asm volatile("v_cvt_pk_bf16_f32 %0, %1, %2" : "=v"(r) : "v"(lo), "v"(hi)); return r; }
; #define LAS __attribute__((address_space(3)))
; __device__ __forceinline__ float bf2f(unsigned b) { return __uint_as_float(b << 16); }
; __device__ __forceinline__ unsigned f2bf(float f) { unsigned u = __float_as_uint(f); u += 0x7FFFu + ((u >> 16) & 1u); return u >> 16; }
; __device__ __forceinline__ float silu_f(float x) { return x * __builtin_amdgcn_rcpf(1.0f + __builtin_amdgcn_exp2f(-1.4426950408889634f * x)); }
; __device__ __forceinline__ void dprep_unit(const Ctx& c, int l, int b, int chunk, int h) {
;     ...
;         for (int i = 0; i < 8; ++i) {
;             const int tt = 8 * wave + i;
;             float q0 = 0.f, q1 = 0.f, k0 = 0.f, k1 = 0.f, v0 = 0.f, v1 = 0.f;
; #pragma unroll
;             for (int j = 0; j < 4; ++j) {
;                 q0 += wq[j][0] * bf2f(xq[i + j] & 0xffffu); q1 += wq[j][1] * bf2f(xq[i + j] >> 16);
;                 k0 += wk[j][0] * bf2f(xk[i + j] & 0xffffu); k1 += wk[j][1] * bf2f(xk[i + j] >> 16);
;                 v0 += wv[j][0] * bf2f(xv[i + j] & 0xffffu); v1 += wv[j][1] * bf2f(xv[i + j] >> 16);
;             }
;             q0 = silu_f(q0); q1 = silu_f(q1); k0 = silu_f(k0); k1 = silu_f(k1); v0 = silu_f(v0); v1 = silu_f(v1);
;             const float rq = rsqrtf(wave_sum(q0 * q0 + q1 * q1) + 1e-6f), rk = rsqrtf(wave_sum(k0 * k0 + k1 * k1) + 1e-6f);
;             q0 *= rq; q1 *= rq; k0 *= rk; k1 *= rk;
;             const float G = Gs[tt], be = betas[tt], eG = __expf(G), eGl = __expf(Gl - G);
;             ((LAS unsigned*)qs)[tt * 72 + lane] = pg8::cvt_pk_bf16(q0, q1);
;             ((LAS unsigned*)ks)[tt * 72 + lane] = pg8::cvt_pk_bf16(k0, k1);
;             *(LAS f32x2*)(rhs + tt * 256 + 2 * lane) = (f32x2){v0 * be, v1 * be};
;             *(LAS f32x2*)(rhs + tt * 256 + 128 + 2 * lane) = (f32x2){k0 * be * eG, k1 * be * eG};
;             ((LAS bf16*)kgT)[(2 * lane) * (REC_PK / 2) + tt] = (bf16)f2bf(k0 * eGl);
;             ((LAS bf16*)kgT)[(2 * lane + 1) * (REC_PK / 2) + tt] = (bf16)f2bf(k1 * eGl);
;             const float sq = 0.08838834764831845f * eG;
;             QGr[tt * (REC_PW / 4) + lane] = pg8::cvt_pk_bf16(q0 * sq, q1 * sq);
;         }
	v_cmp_gt_f32_e32 vcc, s28, v94
	v_pk_mul_f32 v[2:3], v[0:1], v[0:1]
	v_lshlrev_b32_e32 v68, 16, v69
	v_cndmask_b32_e32 v94, v94, v118, vcc
	v_rsq_f32_e32 v94, v94
	v_add_f32_e32 v2, v2, v3
	v_and_b32_e32 v69, 0xffff0000, v69
	v_pk_fma_f32 v[8:9], v[42:43], v[18:19], v[8:9]
	v_mul_f32_e32 v95, 0x45800000, v94
	v_cndmask_b32_e32 v94, v94, v95, vcc
	v_pk_mul_f32 v[94:95], v[108:109], v[94:95] op_sel_hi:[1,0]
	v_add_f32_dpp v2, v2, v2 quad_perm:[1,0,3,2] row_mask:0xf bank_mask:0xf bound_ctrl:1
	v_cvt_pk_bf16_f32 v108, v94, v95
	ds_write_b32 v186, v108
	v_pk_mul_f32 v[108:109], v[110:111], v[94:95] op_sel_hi:[0,1]
	v_pk_mul_f32 v[108:109], v[114:115], v[108:109] op_sel_hi:[0,1]
	v_mul_f32_e32 v94, v115, v94
	ds_write2st64_b64 v187, v[112:113], v[108:109] offset1:1
	v_bfe_u32 v108, v94, 16, 1
	v_add3_u32 v94, v94, v108, s33
	ds_write_b16_d16_hi v149, v94 offset:4
	v_mul_f32_e32 v94, v115, v95
	v_bfe_u32 v95, v94, 16, 1
	v_add3_u32 v94, v94, v95, s33
	ds_write_b16_d16_hi v149, v94 offset:140
	v_mul_f32_e32 v94, v122, v111
	v_mul_f32_e32 v95, v116, v111
	v_cvt_pk_bf16_f32 v108, v94, v95
	global_store_dword v[106:107], v108, off
	v_mul_f32_e32 v107, 0xbfb8aa3b, v80
	v_exp_f32_e32 v107, v107
	v_mul_f32_e32 v108, 0xbfb8aa3b, v81
	v_exp_f32_e32 v109, v108
	ds_read2_b32 v[94:95], v173 offset0:3 offset1:67
	v_add_f32_e32 v107, 1.0, v107
	v_rcp_f32_e32 v108, v107
	v_add_f32_e32 v107, 1.0, v109
	v_rcp_f32_e32 v109, v107
	s_waitcnt lgkmcnt(0)
	v_mul_f32_e32 v106, 0x3fb8aa3b, v94
	v_sub_f32_e32 v94, v63, v94
	v_mul_f32_e32 v94, 0x3fb8aa3b, v94
	v_pk_mul_f32 v[80:81], v[80:81], v[108:109]
	v_exp_f32_e32 v107, v94
	v_pk_mul_f32 v[108:109], v[80:81], v[80:81]
	v_exp_f32_e32 v106, v106
	v_add_f32_e32 v94, v108, v109
	v_add_f32_dpp v2, v2, v2 quad_perm:[2,3,0,1] row_mask:0xf bank_mask:0xf bound_ctrl:1
	v_pk_fma_f32 v[8:9], v[44:45], v[68:69], v[8:9]
	v_add_f32_dpp v94, v94, v94 quad_perm:[1,0,3,2] row_mask:0xf bank_mask:0xf bound_ctrl:1
	v_mul_f32_e32 v110, 0x3db504f3, v106
	v_add_f32_dpp v2, v2, v2 row_half_mirror row_mask:0xf bank_mask:0xf bound_ctrl:1
	v_add_f32_dpp v94, v94, v94 quad_perm:[2,3,0,1] row_mask:0xf bank_mask:0xf bound_ctrl:1
	v_mul_f32_e32 v12, 0xbfb8aa3b, v8
	v_add_f32_dpp v2, v2, v2 row_mirror row_mask:0xf bank_mask:0xf bound_ctrl:1
	v_add_f32_dpp v94, v94, v94 row_half_mirror row_mask:0xf bank_mask:0xf bound_ctrl:1
	v_mul_f32_e32 v13, 0xbfb8aa3b, v9
	v_lshl_add_u64 v[20:21], v[20:21], 2, s[0:1]
	v_add_f32_dpp v94, v94, v94 row_mirror row_mask:0xf bank_mask:0xf bound_ctrl:1
	v_exp_f32_e32 v12, v12
	v_readlane_b32 s10, v94, 16
	v_readlane_b32 s11, v94, 48
	v_readlane_b32 s8, v94, 0
	v_readlane_b32 s9, v94, 32
	v_mov_b32_e32 v108, s10
	v_mov_b32_e32 v109, s11
	v_pk_add_f32 v[108:109], s[8:9], v[108:109]
	v_exp_f32_e32 v13, v13
	v_add_f32_e32 v94, v108, v109
	v_add_f32_e32 v94, 0x358637bd, v94
	v_mul_f32_e32 v108, 0x4b800000, v94
	v_cmp_gt_f32_e32 vcc, s28, v94
	v_add_f32_e32 v12, 1.0, v12
	v_add_f32_e32 v13, 1.0, v13
	v_cndmask_b32_e32 v94, v94, v108, vcc
	v_rsq_f32_e32 v108, v94
	v_mov_b32_e32 v94, v95
	v_pk_mul_f32 v[104:105], v[104:105], v[94:95] op_sel_hi:[1,0]
	v_rcp_f32_e32 v12, v12
	v_mul_f32_e32 v95, 0x45800000, v108
	v_cndmask_b32_e32 v95, v108, v95, vcc
	v_mul_f32_e32 v111, v80, v95
	v_add_f32_dpp v80, v184, v184 quad_perm:[1,0,3,2] row_mask:0xf bank_mask:0xf bound_ctrl:1
	v_rcp_f32_e32 v13, v13
	v_add_u32_e32 v18, v172, v152
	v_add_f32_dpp v80, v80, v80 quad_perm:[2,3,0,1] row_mask:0xf bank_mask:0xf bound_ctrl:1
	v_add_u32_e32 v7, v171, v152
	v_pk_mul_f32 v[4:5], v[8:9], v[12:13]
	v_add_f32_dpp v80, v80, v80 row_half_mirror row_mask:0xf bank_mask:0xf bound_ctrl:1
	v_readlane_b32 s34, v252, 9
	v_lshl_add_u32 v12, v117, 2, v169
	v_add_f32_dpp v80, v80, v80 row_mirror row_mask:0xf bank_mask:0xf bound_ctrl:1
	v_add_u32_e32 v14, v169, v159
	v_readlane_b32 s10, v80, 16
	v_readlane_b32 s11, v80, 48
	v_readlane_b32 s8, v80, 0
	v_readlane_b32 s9, v80, 32
	v_mov_b32_e32 v108, s10
	v_mov_b32_e32 v109, s11
	v_pk_add_f32 v[108:109], s[8:9], v[108:109]
	v_add_u32_e32 v15, v171, v160
	v_add_f32_e32 v80, v108, v109
	v_add_f32_e32 v80, 0x358637bd, v80
	v_mul_f32_e32 v108, 0x4b800000, v80
	v_cmp_gt_f32_e32 vcc, s28, v80
	v_readlane_b32 s35, v252, 10
	s_movk_i32 s13, 0x33ff
	v_cndmask_b32_e32 v80, v80, v108, vcc
	v_rsq_f32_e32 v80, v80
	v_mul_f32_e32 v108, v81, v95
	v_cvt_pk_bf16_f32 v81, v111, v108
	ds_write_b32 v181, v81
	v_mul_f32_e32 v81, 0x45800000, v80
	v_cndmask_b32_e32 v80, v80, v81, vcc
	v_pk_mul_f32 v[80:81], v[100:101], v[80:81] op_sel_hi:[1,0]
	s_mov_b32 s43, 0x10100
	v_cvt_pk_bf16_f32 v95, v80, v81
	ds_write_b32 v182, v95
	v_pk_mul_f32 v[94:95], v[94:95], v[80:81] op_sel_hi:[0,1]
	v_pk_mul_f32 v[94:95], v[106:107], v[94:95] op_sel_hi:[0,1]
	v_mul_f32_e32 v80, v107, v80
	ds_write2st64_b64 v183, v[104:105], v[94:95] offset1:1
	v_bfe_u32 v94, v80, 16, 1
	v_add3_u32 v80, v80, v94, s33
	ds_write_b16_d16_hi v149, v80 offset:6
	v_mul_f32_e32 v80, v107, v81
	v_bfe_u32 v81, v80, 16, 1
	v_add3_u32 v80, v80, v81, s33
	ds_write_b16_d16_hi v149, v80 offset:142
	v_mul_f32_e32 v80, v111, v110
	v_mul_f32_e32 v81, v108, v110
	v_cvt_pk_bf16_f32 v94, v80, v81
	ds_read2_b32 v[80:81], v173 offset0:4 offset1:68
	global_store_dword v[98:99], v94, off
	s_waitcnt lgkmcnt(0)
; __device__ __forceinline__ unsigned cvt_pk_bf16(float lo, float hi) { unsigned r; asm volatile("v_cvt_pk_bf16_f32 %0, %1, %2" : "=v"(r) : "v"(lo), "v"(hi)); return r; }
; #define LAS __attribute__((address_space(3)))
; __device__ __forceinline__ float bf2f(unsigned b) { return __uint_as_float(b << 16); }
; __device__ __forceinline__ unsigned f2bf(float f) { unsigned u = __float_as_uint(f); u += 0x7FFFu + ((u >> 16) & 1u); return u >> 16; }
; __device__ __forceinline__ float silu_f(float x) { return x * __builtin_amdgcn_rcpf(1.0f + __builtin_amdgcn_exp2f(-1.4426950408889634f * x)); }
; __device__ __forceinline__ void dprep_unit(const Ctx& c, int l, int b, int chunk, int h) {
;     ...
;         for (int i = 0; i < 8; ++i) {
;             const int tt = 8 * wave + i;
;             float q0 = 0.f, q1 = 0.f, k0 = 0.f, k1 = 0.f, v0 = 0.f, v1 = 0.f;
; #pragma unroll
;             for (int j = 0; j < 4; ++j) {
;                 q0 += wq[j][0] * bf2f(xq[i + j] & 0xffffu); q1 += wq[j][1] * bf2f(xq[i + j] >> 16);
;                 k0 += wk[j][0] * bf2f(xk[i + j] & 0xffffu); k1 += wk[j][1] * bf2f(xk[i + j] >> 16);
;                 v0 += wv[j][0] * bf2f(xv[i + j] & 0xffffu); v1 += wv[j][1] * bf2f(xv[i + j] >> 16);
;             }
;             q0 = silu_f(q0); q1 = silu_f(q1); k0 = silu_f(k0); k1 = silu_f(k1); v0 = silu_f(v0); v1 = silu_f(v1);
;             const float rq = rsqrtf(wave_sum(q0 * q0 + q1 * q1) + 1e-6f), rk = rsqrtf(wave_sum(k0 * k0 + k1 * k1) + 1e-6f);
;             q0 *= rq; q1 *= rq; k0 *= rk; k1 *= rk;
;             const float G = Gs[tt], be = betas[tt], eG = __expf(G), eGl = __expf(Gl - G);
;             ((LAS unsigned*)qs)[tt * 72 + lane] = pg8::cvt_pk_bf16(q0, q1);
;             ((LAS unsigned*)ks)[tt * 72 + lane] = pg8::cvt_pk_bf16(k0, k1);
;             *(LAS f32x2*)(rhs + tt * 256 + 2 * lane) = (f32x2){v0 * be, v1 * be};
;             *(LAS f32x2*)(rhs + tt * 256 + 128 + 2 * lane) = (f32x2){k0 * be * eG, k1 * be * eG};
;             ((LAS bf16*)kgT)[(2 * lane) * (REC_PK / 2) + tt] = (bf16)f2bf(k0 * eGl);
;             ((LAS bf16*)kgT)[(2 * lane + 1) * (REC_PK / 2) + tt] = (bf16)f2bf(k1 * eGl);
;             const float sq = 0.08838834764831845f * eG;
;             QGr[tt * (REC_PW / 4) + lane] = pg8::cvt_pk_bf16(q0 * sq, q1 * sq);
;         }
	v_mul_f32_e32 v82, 0x3fb8aa3b, v80
	v_sub_f32_e32 v80, v63, v80
	v_mul_f32_e32 v80, 0x3fb8aa3b, v80
	v_exp_f32_e32 v83, v80
	v_add_f32_e32 v80, v90, v91
	v_exp_f32_e32 v82, v82
	s_nop 0
	v_add_f32_dpp v80, v80, v80 quad_perm:[1,0,3,2] row_mask:0xf bank_mask:0xf bound_ctrl:1
	s_nop 1
	v_add_f32_dpp v80, v80, v80 quad_perm:[2,3,0,1] row_mask:0xf bank_mask:0xf bound_ctrl:1
	s_nop 1
	v_add_f32_dpp v80, v80, v80 row_half_mirror row_mask:0xf bank_mask:0xf bound_ctrl:1
	s_nop 1
	v_add_f32_dpp v80, v80, v80 row_mirror row_mask:0xf bank_mask:0xf bound_ctrl:1
	s_nop 0
	v_readlane_b32 s10, v80, 16
	v_readlane_b32 s11, v80, 48
	v_readlane_b32 s8, v80, 0
	v_readlane_b32 s9, v80, 32
	v_mov_b32_e32 v90, s10
	v_mov_b32_e32 v91, s11
	v_pk_add_f32 v[90:91], s[8:9], v[90:91]
	s_nop 0
	v_add_f32_e32 v80, v90, v91
	v_add_f32_e32 v80, 0x358637bd, v80
	v_mul_f32_e32 v90, 0x4b800000, v80
	v_cmp_gt_f32_e32 vcc, s28, v80
	s_nop 1
	v_cndmask_b32_e32 v80, v80, v90, vcc
	v_rsq_f32_e32 v94, v80
	v_mov_b32_e32 v80, v81
	v_pk_mul_f32 v[90:91], v[96:97], v[80:81] op_sel_hi:[1,0]
	v_mul_f32_e32 v96, 0x3db504f3, v82
	v_mul_f32_e32 v81, 0x45800000, v94
	v_cndmask_b32_e32 v81, v94, v81, vcc
	v_mul_f32_e32 v97, v72, v81
	v_add_f32_dpp v72, v180, v180 quad_perm:[1,0,3,2] row_mask:0xf bank_mask:0xf bound_ctrl:1
	s_nop 1
	v_add_f32_dpp v72, v72, v72 quad_perm:[2,3,0,1] row_mask:0xf bank_mask:0xf bound_ctrl:1
	s_nop 1
	v_add_f32_dpp v72, v72, v72 row_half_mirror row_mask:0xf bank_mask:0xf bound_ctrl:1
	s_nop 1
	v_add_f32_dpp v72, v72, v72 row_mirror row_mask:0xf bank_mask:0xf bound_ctrl:1
	s_nop 0
	v_readlane_b32 s10, v72, 16
	v_readlane_b32 s11, v72, 48
	v_readlane_b32 s8, v72, 0
	v_readlane_b32 s9, v72, 32
	v_mov_b32_e32 v94, s10
	v_mov_b32_e32 v95, s11
	v_pk_add_f32 v[94:95], s[8:9], v[94:95]
	s_nop 0
	v_add_f32_e32 v72, v94, v95
	v_add_f32_e32 v72, 0x358637bd, v72
	v_mul_f32_e32 v94, 0x4b800000, v72
	v_cmp_gt_f32_e32 vcc, s28, v72
	s_nop 1
	v_cndmask_b32_e32 v72, v72, v94, vcc
	v_rsq_f32_e32 v72, v72
	v_mul_f32_e32 v94, v73, v81
	v_cvt_pk_bf16_f32 v73, v97, v94
	ds_write_b32 v176, v73
	v_mul_f32_e32 v73, 0x45800000, v72
	v_cndmask_b32_e32 v72, v72, v73, vcc
	v_pk_mul_f32 v[72:73], v[92:93], v[72:73] op_sel_hi:[1,0]
	s_nop 0
	v_cvt_pk_bf16_f32 v81, v72, v73
	ds_write_b32 v178, v81
	v_pk_mul_f32 v[80:81], v[80:81], v[72:73] op_sel_hi:[0,1]
	v_pk_mul_f32 v[80:81], v[82:83], v[80:81] op_sel_hi:[0,1]
	v_mul_f32_e32 v72, v83, v72
	ds_write2st64_b64 v179, v[90:91], v[80:81] offset1:1
	v_bfe_u32 v80, v72, 16, 1
	v_add3_u32 v72, v72, v80, s33
	ds_write_b16_d16_hi v149, v72 offset:8
	v_mul_f32_e32 v80, v83, v73
	v_pk_fma_f32 v[72:73], v[50:51], v[54:55], v[120:121]
	v_bfe_u32 v81, v80, 16, 1
	v_pk_fma_f32 v[72:73], v[52:53], v[56:57], v[72:73]
	v_add3_u32 v90, v80, v81, s33
	v_mul_f32_e32 v82, 0xbfb8aa3b, v72
	v_mul_f32_e32 v83, 0xbfb8aa3b, v73
	v_exp_f32_e32 v82, v82
	v_exp_f32_e32 v83, v83
	ds_write_b16_d16_hi v149, v90 offset:144
	v_add_f32_e32 v80, 1.0, v82
	v_add_f32_e32 v81, 1.0, v83
	v_rcp_f32_e32 v80, v80
	v_rcp_f32_e32 v81, v81
	v_mul_f32_e32 v82, v97, v96
	v_mul_f32_e32 v83, v94, v96
	v_pk_mul_f32 v[72:73], v[72:73], v[80:81]
	s_nop 0
	v_pk_mul_f32 v[80:81], v[72:73], v[72:73]
	s_nop 0
	v_add_f32_e32 v80, v80, v81
	s_nop 1
	v_add_f32_dpp v80, v80, v80 quad_perm:[1,0,3,2] row_mask:0xf bank_mask:0xf bound_ctrl:1
	s_nop 1
	v_add_f32_dpp v80, v80, v80 quad_perm:[2,3,0,1] row_mask:0xf bank_mask:0xf bound_ctrl:1
	s_nop 1
	v_add_f32_dpp v80, v80, v80 row_half_mirror row_mask:0xf bank_mask:0xf bound_ctrl:1
	s_nop 1
	v_add_f32_dpp v80, v80, v80 row_mirror row_mask:0xf bank_mask:0xf bound_ctrl:1
	s_nop 0
	v_readlane_b32 s10, v80, 16
	v_readlane_b32 s11, v80, 48
	v_readlane_b32 s8, v80, 0
	v_readlane_b32 s9, v80, 32
	v_mov_b32_e32 v80, s10
	v_mov_b32_e32 v81, s11
	v_pk_add_f32 v[80:81], s[8:9], v[80:81]
	s_nop 0
	v_add_f32_e32 v80, v80, v81
	v_add_f32_e32 v80, 0x358637bd, v80
	v_mul_f32_e32 v81, 0x4b800000, v80
	v_cmp_gt_f32_e32 vcc, s28, v80
	s_nop 1
	v_cndmask_b32_e32 v80, v80, v81, vcc
	v_rsq_f32_e32 v90, v80
	v_cvt_pk_bf16_f32 v80, v82, v83
	global_store_dword v[84:85], v80, off
	ds_read2_b32 v[80:81], v173 offset0:5 offset1:69
	v_mul_f32_e32 v82, 0x45800000, v90
	v_cndmask_b32_e32 v82, v90, v82, vcc
	v_mul_f32_e32 v90, v72, v82
	v_mul_f32_e32 v73, v73, v82
	v_add_f32_dpp v82, v177, v177 quad_perm:[1,0,3,2] row_mask:0xf bank_mask:0xf bound_ctrl:1
	s_waitcnt lgkmcnt(0)
; __device__ __forceinline__ unsigned cvt_pk_bf16(float lo, float hi) { unsigned r; asm volatile("v_cvt_pk_bf16_f32 %0, %1, %2" : "=v"(r) : "v"(lo), "v"(hi)); return r; }
; #define LAS __attribute__((address_space(3)))
; __device__ __forceinline__ float bf2f(unsigned b) { return __uint_as_float(b << 16); }
; __device__ __forceinline__ unsigned f2bf(float f) { unsigned u = __float_as_uint(f); u += 0x7FFFu + ((u >> 16) & 1u); return u >> 16; }
; __device__ __forceinline__ float silu_f(float x) { return x * __builtin_amdgcn_rcpf(1.0f + __builtin_amdgcn_exp2f(-1.4426950408889634f * x)); }
; __device__ __forceinline__ void dprep_unit(const Ctx& c, int l, int b, int chunk, int h) {
;     ...
;         for (int i = 0; i < 8; ++i) {
;             const int tt = 8 * wave + i;
;             float q0 = 0.f, q1 = 0.f, k0 = 0.f, k1 = 0.f, v0 = 0.f, v1 = 0.f;
; #pragma unroll
;             for (int j = 0; j < 4; ++j) {
;                 q0 += wq[j][0] * bf2f(xq[i + j] & 0xffffu); q1 += wq[j][1] * bf2f(xq[i + j] >> 16);
;                 k0 += wk[j][0] * bf2f(xk[i + j] & 0xffffu); k1 += wk[j][1] * bf2f(xk[i + j] >> 16);
;                 v0 += wv[j][0] * bf2f(xv[i + j] & 0xffffu); v1 += wv[j][1] * bf2f(xv[i + j] >> 16);
;             }
;             q0 = silu_f(q0); q1 = silu_f(q1); k0 = silu_f(k0); k1 = silu_f(k1); v0 = silu_f(v0); v1 = silu_f(v1);
;             const float rq = rsqrtf(wave_sum(q0 * q0 + q1 * q1) + 1e-6f), rk = rsqrtf(wave_sum(k0 * k0 + k1 * k1) + 1e-6f);
;             q0 *= rq; q1 *= rq; k0 *= rk; k1 *= rk;
;             const float G = Gs[tt], be = betas[tt], eG = __expf(G), eGl = __expf(Gl - G);
;             ((LAS unsigned*)qs)[tt * 72 + lane] = pg8::cvt_pk_bf16(q0, q1);
;             ((LAS unsigned*)ks)[tt * 72 + lane] = pg8::cvt_pk_bf16(k0, k1);
;             *(LAS f32x2*)(rhs + tt * 256 + 2 * lane) = (f32x2){v0 * be, v1 * be};
;             *(LAS f32x2*)(rhs + tt * 256 + 128 + 2 * lane) = (f32x2){k0 * be * eG, k1 * be * eG};
;             ((LAS bf16*)kgT)[(2 * lane) * (REC_PK / 2) + tt] = (bf16)f2bf(k0 * eGl);
;             ((LAS bf16*)kgT)[(2 * lane + 1) * (REC_PK / 2) + tt] = (bf16)f2bf(k1 * eGl);
;             const float sq = 0.08838834764831845f * eG;
;             QGr[tt * (REC_PW / 4) + lane] = pg8::cvt_pk_bf16(q0 * sq, q1 * sq);
;         }
	v_mul_f32_e32 v72, 0x3fb8aa3b, v80
	v_sub_f32_e32 v80, v63, v80
	v_add_f32_dpp v82, v82, v82 quad_perm:[2,3,0,1] row_mask:0xf bank_mask:0xf bound_ctrl:1
	v_mul_f32_e32 v80, 0x3fb8aa3b, v80
	v_exp_f32_e32 v91, v80
	v_add_f32_dpp v82, v82, v82 row_half_mirror row_mask:0xf bank_mask:0xf bound_ctrl:1
	v_cvt_pk_bf16_f32 v80, v90, v73
	ds_write_b32 v174, v80
	v_mov_b32_e32 v80, v81
	v_add_f32_dpp v82, v82, v82 row_mirror row_mask:0xf bank_mask:0xf bound_ctrl:1
	v_exp_f32_e32 v72, v72
	v_readlane_b32 s10, v82, 16
	v_readlane_b32 s11, v82, 48
	v_readlane_b32 s8, v82, 0
	v_readlane_b32 s9, v82, 32
	v_mov_b32_e32 v82, s10
	v_mov_b32_e32 v83, s11
	v_pk_add_f32 v[82:83], s[8:9], v[82:83]
	s_nop 0
	v_add_f32_e32 v82, v82, v83
	v_add_f32_e32 v82, 0x358637bd, v82
	v_mul_f32_e32 v83, 0x4b800000, v82
	v_cmp_gt_f32_e32 vcc, s28, v82
	s_nop 1
	v_cndmask_b32_e32 v82, v82, v83, vcc
	v_rsq_f32_e32 v84, v82
	v_pk_mul_f32 v[82:83], v[86:87], v[80:81] op_sel_hi:[1,0]
	v_mul_f32_e32 v81, 0x45800000, v84
	v_cndmask_b32_e32 v84, v84, v81, vcc
	v_pk_mul_f32 v[84:85], v[88:89], v[84:85] op_sel_hi:[1,0]
	s_nop 0
	v_cvt_pk_bf16_f32 v81, v84, v85
	ds_write_b32 v175, v81
	v_pk_mul_f32 v[80:81], v[80:81], v[84:85] op_sel_hi:[0,1]
	v_pk_mul_f32 v[80:81], v[72:73], v[80:81] op_sel_hi:[0,1]
	ds_write2st64_b64 v150, v[82:83], v[80:81] offset1:1
	v_mul_f32_e32 v80, v91, v84
	v_bfe_u32 v81, v80, 16, 1
	v_add3_u32 v80, v80, v81, s33
	ds_write_b16_d16_hi v149, v80 offset:10
	v_mul_f32_e32 v80, v91, v85
	v_bfe_u32 v81, v80, 16, 1
	v_add3_u32 v82, v80, v81, s33
	v_pk_fma_f32 v[80:81], v[48:49], v[54:55], v[102:103]
	ds_write_b16_d16_hi v149, v82 offset:146
	v_pk_fma_f32 v[80:81], v[50:51], v[56:57], v[80:81]
	v_mul_f32_e32 v72, 0x3db504f3, v72
	v_pk_fma_f32 v[80:81], v[52:53], v[58:59], v[80:81]
	v_mul_f32_e32 v85, v73, v72
	v_mul_f32_e32 v83, 0xbfb8aa3b, v80
	v_mul_f32_e32 v84, 0xbfb8aa3b, v81
	v_exp_f32_e32 v83, v83
	v_exp_f32_e32 v84, v84
	v_mul_f32_e32 v48, 0xbfb8aa3b, v46
	v_mul_f32_e32 v49, 0xbfb8aa3b, v47
	v_add_f32_e32 v82, 1.0, v83
	v_add_f32_e32 v83, 1.0, v84
	v_rcp_f32_e32 v82, v82
	v_rcp_f32_e32 v83, v83
	v_mul_f32_e32 v84, v90, v72
	v_exp_f32_e32 v48, v48
	v_exp_f32_e32 v49, v49
	v_pk_mul_f32 v[72:73], v[80:81], v[82:83]
	v_add_f32_e32 v48, 1.0, v48
	v_pk_mul_f32 v[80:81], v[72:73], v[72:73]
	v_add_f32_e32 v49, 1.0, v49
	v_add_f32_e32 v80, v80, v81
	v_rcp_f32_e32 v48, v48
	v_rcp_f32_e32 v49, v49
	v_add_f32_dpp v80, v80, v80 quad_perm:[1,0,3,2] row_mask:0xf bank_mask:0xf bound_ctrl:1
	v_pk_mul_f32 v[46:47], v[46:47], v[48:49]
	s_nop 0
	v_add_f32_dpp v80, v80, v80 quad_perm:[2,3,0,1] row_mask:0xf bank_mask:0xf bound_ctrl:1
	v_pk_mul_f32 v[48:49], v[46:47], v[46:47]
	s_nop 0
	v_add_f32_dpp v80, v80, v80 row_half_mirror row_mask:0xf bank_mask:0xf bound_ctrl:1
	v_add_f32_e32 v48, v48, v49
	s_nop 0
	v_add_f32_dpp v80, v80, v80 row_mirror row_mask:0xf bank_mask:0xf bound_ctrl:1
	v_add_f32_dpp v48, v48, v48 quad_perm:[1,0,3,2] row_mask:0xf bank_mask:0xf bound_ctrl:1
	v_readlane_b32 s10, v80, 16
	v_readlane_b32 s11, v80, 48
	v_readlane_b32 s8, v80, 0
	v_readlane_b32 s9, v80, 32
	v_mov_b32_e32 v80, s10
	v_mov_b32_e32 v81, s11
	v_pk_add_f32 v[80:81], s[8:9], v[80:81]
	v_add_f32_dpp v48, v48, v48 quad_perm:[2,3,0,1] row_mask:0xf bank_mask:0xf bound_ctrl:1
	v_add_f32_e32 v80, v80, v81
	v_add_f32_e32 v80, 0x358637bd, v80
	v_mul_f32_e32 v81, 0x4b800000, v80
	v_cmp_gt_f32_e32 vcc, s28, v80
	v_add_f32_dpp v48, v48, v48 row_half_mirror row_mask:0xf bank_mask:0xf bound_ctrl:1
	s_nop 0
	v_cndmask_b32_e32 v80, v80, v81, vcc
	v_rsq_f32_e32 v80, v80
	v_cvt_pk_bf16_f32 v81, v84, v85
	global_store_dword v[74:75], v81, off
	ds_read2_b32 v[74:75], v173 offset0:6 offset1:70
	v_mul_f32_e32 v81, 0x45800000, v80
	v_cndmask_b32_e32 v80, v80, v81, vcc
	v_mul_f32_e32 v82, v72, v80
	v_mul_f32_e32 v73, v73, v80
	v_add_f32_dpp v80, v148, v148 quad_perm:[1,0,3,2] row_mask:0xf bank_mask:0xf bound_ctrl:1
	s_waitcnt lgkmcnt(0)
; __device__ __forceinline__ unsigned cvt_pk_bf16(float lo, float hi) { unsigned r; asm volatile("v_cvt_pk_bf16_f32 %0, %1, %2" : "=v"(r) : "v"(lo), "v"(hi)); return r; }
; #define LAS __attribute__((address_space(3)))
; __device__ __forceinline__ float bf2f(unsigned b) { return __uint_as_float(b << 16); }
; __device__ __forceinline__ unsigned f2bf(float f) { unsigned u = __float_as_uint(f); u += 0x7FFFu + ((u >> 16) & 1u); return u >> 16; }
; __device__ __forceinline__ void dprep_unit(const Ctx& c, int l, int b, int chunk, int h) {
;     ...
;         for (int i = 0; i < 8; ++i) {
;             const int tt = 8 * wave + i;
;             float q0 = 0.f, q1 = 0.f, k0 = 0.f, k1 = 0.f, v0 = 0.f, v1 = 0.f;
; #pragma unroll
;             for (int j = 0; j < 4; ++j) {
;                 q0 += wq[j][0] * bf2f(xq[i + j] & 0xffffu); q1 += wq[j][1] * bf2f(xq[i + j] >> 16);
;                 k0 += wk[j][0] * bf2f(xk[i + j] & 0xffffu); k1 += wk[j][1] * bf2f(xk[i + j] >> 16);
;                 v0 += wv[j][0] * bf2f(xv[i + j] & 0xffffu); v1 += wv[j][1] * bf2f(xv[i + j] >> 16);
;             }
;             q0 = silu_f(q0); q1 = silu_f(q1); k0 = silu_f(k0); k1 = silu_f(k1); v0 = silu_f(v0); v1 = silu_f(v1);
;             const float rq = rsqrtf(wave_sum(q0 * q0 + q1 * q1) + 1e-6f), rk = rsqrtf(wave_sum(k0 * k0 + k1 * k1) + 1e-6f);
;             q0 *= rq; q1 *= rq; k0 *= rk; k1 *= rk;
;             const float G = Gs[tt], be = betas[tt], eG = __expf(G), eGl = __expf(Gl - G);
;             ((LAS unsigned*)qs)[tt * 72 + lane] = pg8::cvt_pk_bf16(q0, q1);
;             ((LAS unsigned*)ks)[tt * 72 + lane] = pg8::cvt_pk_bf16(k0, k1);
;             *(LAS f32x2*)(rhs + tt * 256 + 2 * lane) = (f32x2){v0 * be, v1 * be};
;             *(LAS f32x2*)(rhs + tt * 256 + 128 + 2 * lane) = (f32x2){k0 * be * eG, k1 * be * eG};
;             ((LAS bf16*)kgT)[(2 * lane) * (REC_PK / 2) + tt] = (bf16)f2bf(k0 * eGl);
;             ((LAS bf16*)kgT)[(2 * lane + 1) * (REC_PK / 2) + tt] = (bf16)f2bf(k1 * eGl);
;             const float sq = 0.08838834764831845f * eG;
;             QGr[tt * (REC_PW / 4) + lane] = pg8::cvt_pk_bf16(q0 * sq, q1 * sq);
;         }
; __device__ __forceinline__ void m1_dispatch(const Ctx& c, int l, int u) {
;     ...
;         dprep_unit(c, l, u >> 8, (u >> 3) & 31, u & 7); __syncthreads(); dprep_unit(c, l, u >> 8, (u >> 3) & 31, (u & 7) + 8);
	v_mul_f32_e32 v72, 0x3fb8aa3b, v74
	v_sub_f32_e32 v74, v63, v74
	v_add_f32_dpp v80, v80, v80 quad_perm:[2,3,0,1] row_mask:0xf bank_mask:0xf bound_ctrl:1
	v_mul_f32_e32 v74, 0x3fb8aa3b, v74
	v_exp_f32_e32 v83, v74
	v_add_f32_dpp v80, v80, v80 row_half_mirror row_mask:0xf bank_mask:0xf bound_ctrl:1
	v_cvt_pk_bf16_f32 v74, v82, v73
	ds_write_b32 v145, v74
	v_mov_b32_e32 v74, v75
	v_add_f32_dpp v80, v80, v80 row_mirror row_mask:0xf bank_mask:0xf bound_ctrl:1
	v_exp_f32_e32 v72, v72
	v_readlane_b32 s10, v80, 16
	v_readlane_b32 s11, v80, 48
	v_readlane_b32 s8, v80, 0
	v_readlane_b32 s9, v80, 32
	v_mov_b32_e32 v80, s10
	v_mov_b32_e32 v81, s11
	v_pk_add_f32 v[80:81], s[8:9], v[80:81]
	v_pk_mul_f32 v[76:77], v[76:77], v[74:75] op_sel_hi:[1,0]
	v_add_f32_e32 v80, v80, v81
	v_add_f32_e32 v80, 0x358637bd, v80
	v_mul_f32_e32 v81, 0x4b800000, v80
	v_cmp_gt_f32_e32 vcc, s28, v80
	v_add_f32_dpp v48, v48, v48 row_mirror row_mask:0xf bank_mask:0xf bound_ctrl:1
	v_mul_f32_e32 v50, 0x3db504f3, v72
	v_cndmask_b32_e32 v80, v80, v81, vcc
	v_rsq_f32_e32 v80, v80
	v_readlane_b32 s10, v48, 16
	v_readlane_b32 s11, v48, 48
	v_readlane_b32 s8, v48, 0
	v_mul_f32_e32 v75, 0x45800000, v80
	v_cndmask_b32_e32 v80, v80, v75, vcc
	v_pk_mul_f32 v[78:79], v[78:79], v[80:81] op_sel_hi:[1,0]
	v_readlane_b32 s9, v48, 32
	v_cvt_pk_bf16_f32 v75, v78, v79
	v_mov_b32_e32 v48, s10
	v_mov_b32_e32 v49, s11
	ds_write_b32 v147, v75
	v_pk_mul_f32 v[74:75], v[74:75], v[78:79] op_sel_hi:[0,1]
	v_pk_add_f32 v[48:49], s[8:9], v[48:49]
	v_pk_mul_f32 v[74:75], v[72:73], v[74:75] op_sel_hi:[0,1]
	v_add_f32_e32 v48, v48, v49
	ds_write2st64_b64 v146, v[76:77], v[74:75] offset1:1
	v_mul_f32_e32 v74, v83, v78
	v_add_f32_e32 v48, 0x358637bd, v48
	v_bfe_u32 v75, v74, 16, 1
	v_mul_f32_e32 v49, 0x4b800000, v48
	v_cmp_gt_f32_e32 vcc, s28, v48
	v_add3_u32 v74, v74, v75, s33
	ds_write_b16_d16_hi v149, v74 offset:12
	v_cndmask_b32_e32 v48, v48, v49, vcc
	v_mul_f32_e32 v74, v83, v79
	v_rsq_f32_e32 v48, v48
	v_readlane_b32 s10, v2, 16
	v_readlane_b32 s11, v2, 48
	v_bfe_u32 v75, v74, 16, 1
	v_readlane_b32 s8, v2, 0
	v_readlane_b32 s9, v2, 32
	v_mov_b32_e32 v2, s10
	v_mov_b32_e32 v3, s11
	v_add3_u32 v74, v74, v75, s33
	v_pk_add_f32 v[2:3], s[8:9], v[2:3]
	ds_write_b16_d16_hi v149, v74 offset:148
	v_mul_f32_e32 v51, v82, v50
	v_mul_f32_e32 v50, v73, v50
	v_cvt_pk_bf16_f32 v49, v51, v50
	v_add_f32_e32 v2, v2, v3
	global_store_dword v[20:21], v49, off
	ds_read2_b32 v[20:21], v173 offset0:7 offset1:71
	v_mul_f32_e32 v49, 0x45800000, v48
	v_add_f32_e32 v2, 0x358637bd, v2
	v_cndmask_b32_e32 v48, v48, v49, vcc
	v_mul_f32_e32 v3, 0x4b800000, v2
	v_cmp_gt_f32_e32 vcc, s28, v2
	v_mul_f32_e32 v49, v46, v48
	s_waitcnt lgkmcnt(0)
	v_mul_f32_e32 v46, 0x3fb8aa3b, v20
	v_cndmask_b32_e32 v2, v2, v3, vcc
	v_rsq_f32_e32 v3, v2
	v_sub_f32_e32 v20, v63, v20
	v_mul_f32_e32 v20, 0x3fb8aa3b, v20
	v_exp_f32_e32 v46, v46
	v_exp_f32_e32 v20, v20
	v_mul_f32_e32 v6, 0x45800000, v3
	v_mov_b32_e32 v2, v21
	v_cndmask_b32_e32 v6, v3, v6, vcc
	v_mul_f32_e32 v47, v47, v48
	v_cvt_pk_bf16_f32 v48, v49, v47
	ds_write_b32 v18, v48
	v_pk_mul_f32 v[4:5], v[4:5], v[2:3] op_sel_hi:[1,0]
	v_pk_mul_f32 v[0:1], v[0:1], v[6:7] op_sel_hi:[1,0]
	v_readlane_b32 s8, v251, 37
	v_cvt_pk_bf16_f32 v3, v0, v1
	ds_write_b32 v7, v3
	v_pk_mul_f32 v[2:3], v[2:3], v[0:1] op_sel_hi:[0,1]
	v_add3_u32 v8, v144, s8, v141
	v_pk_mul_f32 v[2:3], v[46:47], v[2:3] op_sel_hi:[0,1]
	v_mul_f32_e32 v0, v20, v0
	ds_write2st64_b64 v8, v[4:5], v[2:3] offset1:1
	v_bfe_u32 v2, v0, 16, 1
	v_add3_u32 v0, v0, v2, s33
	ds_write_b16_d16_hi v149, v0 offset:14
	v_mul_f32_e32 v0, v20, v1
	v_bfe_u32 v1, v0, 16, 1
	v_add3_u32 v0, v0, v1, s33
	ds_write_b16_d16_hi v149, v0 offset:150
	v_mul_f32_e32 v0, 0x3db504f3, v46
	v_mul_f32_e32 v1, v49, v0
	v_mul_f32_e32 v0, v47, v0
	v_cvt_pk_bf16_f32 v2, v1, v0
	v_lshl_add_u64 v[0:1], v[22:23], 2, s[0:1]
	v_readlane_b32 s0, v251, 38
	v_readlane_b32 s1, v251, 39
	global_store_dword v[0:1], v2, off
	s_mov_b64 s[8:9], 0
	v_cndmask_b32_e64 v0, v172, v171, s[0:1]
	s_add_i32 s0, s39, s40
	s_add_i32 s0, s0, s38
	s_mul_i32 s0, s0, 0x16d00
	s_add_i32 s12, s0, 0x16d0000
	s_add_u32 s0, s51, s12
	s_addc_u32 s1, s52, 0
	v_lshl_add_u64 v[4:5], s[0:1], 0, v[24:25]
	s_add_u32 s0, s53, s12
	s_addc_u32 s1, s54, 0
	v_lshl_add_u64 v[6:7], s[0:1], 0, v[26:27]
	s_add_u32 s0, s55, s12
	s_addc_u32 s1, s56, 0
	v_lshl_add_u64 v[8:9], s[0:1], 0, v[28:29]
	s_add_u32 s0, s57, s12
	s_addc_u32 s1, s58, 0
	v_add_u32_e32 v0, v0, v153
	v_lshl_add_u64 v[10:11], s[0:1], 0, v[30:31]
	v_readlane_b32 s0, v251, 61
	v_add_u32_e32 v18, v0, v134
	v_readlane_b32 s39, v250, 7
	v_add3_u32 v13, v168, s0, v158
	s_mov_b32 s40, 0x42b17218
	s_mov_b32 s38, 0xbfb8aa3b
	s_waitcnt lgkmcnt(0)
	s_barrier
	s_branch .LBB0_1253
.Lmx0_tramp:
	s_branch .LBB0_1029
.LBB0_1251:
	s_or_b64 exec, exec, s[0:1]
	ds_write_b32 v13, v1 offset:768

; __device__ __forceinline__ void phase_M1(Ctx& c, int l, int q, const XcdBarrier& bar) {
;     for (;;) {
;         const int u = next_unit(c, q);
;         if (u >= M1_TOTAL) break;
;         m1_dispatch(c, l, u);
;     }
.LBB0_1338:
	v_readlane_b32 s2, v255, 61
	s_nop 3
	s_cmp_eq_u32 s2, 0
	s_cbranch_scc1 .Lmx0_m2go
	s_mov_b32 s28, s36
	s_branch .LBB0_1599

; __device__ __forceinline__ void phase_M2(Ctx& c, int l, int q, const XcdBarrier& bar) {
;     if ((int)blockIdx.x < M2_NDP) dscan_unit<0>(c, l, (int)blockIdx.x >> 4, (int)blockIdx.x & 15);
;     for (;;) {
;         const int u = next_unit(c, q);
;         const int pskip = ((int)gridDim.x == 256) ? PRO_NMOD : 0;
;         if (u >= M2_TOTAL + (l == 0 ? PRO_N - pskip : 0)) break;
;         if (u < M2_TOTAL) m2_dispatch(c, l, u); else prologue_unit(c, 1, pskip + u - M2_TOTAL);
;     }
.LBB0_1548:
	v_readlane_b32 s2, v255, 61
	s_nop 3
	s_cmp_eq_u32 s2, 0
	s_cbranch_scc0 .Lmx0_m2exit
	v_writelane_b32 v255, 1, 61
	v_readlane_b32 s39, v250, 7
	s_mov_b32 s36, s92
	s_mov_b64 s[0:1], -1
	s_branch .Lmx0_tramp
